# AF32 GEMM k-loops: weight-tile LDS stores and next-step weight loads moved to the head of the k-step, ahead of the f32->bf16 conversion of the activation tile
# speedup vs baseline: 1.0463x; 1.0121x over previous
; #define G_LOAD(kt_) do { \
;     if constexpr (AF32) { _Pragma("unroll") for (int i = 0; i < 4; ++i) ld16_sc1(ra[i], Af + (size_t)i * 32 * lda + (kt_) * 32); } \
;     else { _Pragma("unroll") for (int i = 0; i < 2; ++i) ld16_sc1(rab[i], Ab + (size_t)i * 64 * lda + (kt_) * 32); } \
;     _Pragma("unroll") for (int i = 0; i < 4; ++i) ld16_sc1(rb[i], Bp + (size_t)(kt_) * bstep + i * 2048); } while (0)
; template <bool AF32, class Epi>
; __device__ __forceinline__ void gemm_tile(unsigned char* smem, const void* Ap, int lda, const bf16_t* WT, int N, int K, const Epi& epi, int m0, int n0,
;                                           GPre& pr, bool preloaded, const void* nAp, int nn0, bool has_next) {
;     ...
;   if (!preloaded) G_LOAD(0);
;   G_STORE(0);
;   if (nk > 1) G_LOAD(1);
;   __syncthreads();
;   for (int kt = 0; kt < nk; ++kt) {
;     const int cur = kt & 1;
;     if (kt + 1 < nk) G_STORE(cur ^ 1);
;     if (kt + 2 < nk) G_LOAD(kt + 2);
;     const bf16_t* a_s = sbase + cur * G_STAGE + (wr * 64 + l15) * GLD + quad * 8;
;     const bf16_t* b_s = sbase + cur * G_STAGE + 128 * GLD + (wc * 128 + l15) * GLD + quad * 8;
;     __builtin_amdgcn_s_setprio(1);
;     bf16x8 af[4];
; #pragma unroll
;     for (int m = 0; m < 4; ++m) af[m] = *(const bf16x8*)(a_s + m * 16 * GLD);
; #pragma unroll
;     for (int nh = 0; nh < 4; ++nh) {
;       bf16x8 bfr[2];
; #pragma unroll
;       for (int n2 = 0; n2 < 2; ++n2) bfr[n2] = *(const bf16x8*)(b_s + (nh * 2 + n2) * 16 * GLD);
; #pragma unroll
;       for (int m = 0; m < 4; ++m)
; #pragma unroll
;         for (int n2 = 0; n2 < 2; ++n2) acc[m][nh * 2 + n2] = __builtin_amdgcn_mfma_f32_16x16x32_bf16(bfr[n2], af[m], acc[m][nh * 2 + n2], 0, 0, 0);
;     }
;     __builtin_amdgcn_s_setprio(0);
;     __syncthreads();
;   }
.LBB0_126:
	s_and_b32 s3, s12, 1
	s_waitcnt vmcnt(0)
	s_xor_b32 s4, s3, 1
	s_mulk_i32 s4, 0x7800
	v_lshl_add_u32 v208, v170, 1, s4
	ds_write_b128 v208, v[32:35] offset:10240
	ds_write_b128 v208, v[36:39] offset:15360
	ds_write_b128 v208, v[40:43] offset:20480
	ds_write_b128 v208, v[48:51] offset:25600
	s_setprio 2
	global_load_dwordx4 v[32:35], v[172:173], off sc1
	v_lshl_add_u64 v[192:193], v[172:173], 0, s[30:31]
	global_load_dwordx4 v[36:39], v[192:193], off sc1
	v_lshl_add_u64 v[194:195], v[172:173], 0, s[34:35]
	global_load_dwordx4 v[40:43], v[194:195], off sc1
	v_lshl_add_u64 v[196:197], v[172:173], 0, s[36:37]
	global_load_dwordx4 v[48:51], v[196:197], off sc1
	s_setprio 0
	v_cvt_pk_bf16_f32 v198, v16, v17
	v_mov_b32_e32 v201, v16
	v_mov_b32_e32 v16, v9
	v_lshl_add_u32 v185, v181, 1, s4
	v_cvt_pk_bf16_f32 v199, v18, v19
	v_mov_b32_e32 v200, v8
	v_mov_b32_e32 v202, v10
	v_mov_b32_e32 v203, v18
	v_mov_b32_e32 v18, v11
	v_cvt_pk_bf16_f32 v8, v8, v9
	v_cvt_pk_bf16_f32 v9, v10, v11
	v_cvt_pk_bf16_f32 v10, v4, v5
	v_cvt_pk_bf16_f32 v11, v6, v7
	v_mov_b32_e32 v204, v0
	v_mov_b32_e32 v205, v4
	v_mov_b32_e32 v4, v1
	v_mov_b32_e32 v206, v2
	v_mov_b32_e32 v207, v6
	v_mov_b32_e32 v6, v3
	v_cvt_pk_bf16_f32 v0, v0, v1
	v_cvt_pk_bf16_f32 v1, v2, v3
	v_pk_mul_f32 v[2:3], v[16:17], v[16:17]
	ds_write2st64_b64 v185, v[198:199], v[8:9] offset1:5
	ds_write2st64_b64 v185, v[10:11], v[0:1] offset0:10 offset1:15
	v_pk_fma_f32 v[0:1], v[200:201], v[200:201], v[2:3]
	v_pk_mul_f32 v[4:5], v[4:5], v[4:5]
	v_pk_fma_f32 v[0:1], v[202:203], v[202:203], v[0:1]
	v_pk_fma_f32 v[2:3], v[204:205], v[204:205], v[4:5]
	v_pk_fma_f32 v[198:199], v[18:19], v[18:19], v[0:1]
	s_setprio 2
	global_load_dwordx4 v[16:19], v[174:175], off sc1
	v_lshl_add_u64 v[186:187], v[174:175], 0, s[26:27]
	v_pk_fma_f32 v[2:3], v[206:207], v[206:207], v[2:3]
	global_load_dwordx4 v[8:11], v[186:187], off sc1
	v_lshl_add_u64 v[188:189], v[174:175], 0, s[28:29]
	v_pk_fma_f32 v[200:201], v[6:7], v[6:7], v[2:3]
	global_load_dwordx4 v[4:7], v[188:189], off sc1
	v_lshl_add_u64 v[190:191], v[174:175], 0, s[22:23]
	global_load_dwordx4 v[0:3], v[190:191], off sc1
	s_setprio 0
	s_add_i32 s12, s12, 1
	s_mulk_i32 s3, 0x7800
	v_pk_add_f32 v[168:169], v[168:169], v[198:199]
	v_pk_add_f32 v[164:165], v[164:165], v[200:201]
	v_add3_u32 v185, s3, v166, v184
	s_setprio 1
	v_add3_u32 v212, s3, v183, v184
	ds_read_b128 v[186:189], v212 offset:10240
	ds_read_b128 v[190:193], v212 offset:11520
	ds_read_b128 v[194:197], v185
	ds_read_b128 v[198:201], v185 offset:1280
	ds_read_b128 v[202:205], v185 offset:2560
	ds_read_b128 v[206:209], v185 offset:3840
	s_waitcnt lgkmcnt(3)
	v_mfma_f32_16x16x32_bf16 v[156:159], v[186:189], v[194:197], v[156:159]
	v_mfma_f32_16x16x32_bf16 v[152:155], v[190:193], v[194:197], v[152:155]
	s_waitcnt lgkmcnt(2)
	v_mfma_f32_16x16x32_bf16 v[140:143], v[186:189], v[198:201], v[140:143]
	v_mfma_f32_16x16x32_bf16 v[136:139], v[190:193], v[198:201], v[136:139]
	s_waitcnt lgkmcnt(1)
	v_mfma_f32_16x16x32_bf16 v[108:111], v[186:189], v[202:205], v[108:111]
	v_mfma_f32_16x16x32_bf16 v[100:103], v[190:193], v[202:205], v[100:103]
	s_waitcnt lgkmcnt(0)
	v_mfma_f32_16x16x32_bf16 v[76:79], v[186:189], v[206:209], v[76:79]
	ds_read_b128 v[186:189], v212 offset:12800
	v_mfma_f32_16x16x32_bf16 v[68:71], v[190:193], v[206:209], v[68:71]
	ds_read_b128 v[190:193], v212 offset:14080
	s_waitcnt lgkmcnt(1)
	v_mfma_f32_16x16x32_bf16 v[148:151], v[186:189], v[194:197], v[148:151]
	s_waitcnt lgkmcnt(0)
	v_mfma_f32_16x16x32_bf16 v[144:147], v[190:193], v[194:197], v[144:147]
	v_mfma_f32_16x16x32_bf16 v[124:127], v[186:189], v[198:201], v[124:127]
	v_mfma_f32_16x16x32_bf16 v[116:119], v[190:193], v[198:201], v[116:119]
	v_mfma_f32_16x16x32_bf16 v[92:95], v[186:189], v[202:205], v[92:95]
	v_mfma_f32_16x16x32_bf16 v[84:87], v[190:193], v[202:205], v[84:87]
	v_mfma_f32_16x16x32_bf16 v[60:63], v[186:189], v[206:209], v[60:63]
	ds_read_b128 v[186:189], v212 offset:15360
	v_mfma_f32_16x16x32_bf16 v[52:55], v[190:193], v[206:209], v[52:55]
	ds_read_b128 v[190:193], v212 offset:16640
	s_waitcnt lgkmcnt(1)
	v_mfma_f32_16x16x32_bf16 v[132:135], v[186:189], v[194:197], v[132:135]
	s_waitcnt lgkmcnt(0)
	v_mfma_f32_16x16x32_bf16 v[128:131], v[190:193], v[194:197], v[128:131]
	v_mfma_f32_16x16x32_bf16 v[104:107], v[186:189], v[198:201], v[104:107]
	v_mfma_f32_16x16x32_bf16 v[96:99], v[190:193], v[198:201], v[96:99]
	v_mfma_f32_16x16x32_bf16 v[72:75], v[186:189], v[202:205], v[72:75]
	v_mfma_f32_16x16x32_bf16 v[64:67], v[190:193], v[202:205], v[64:67]
	v_mfma_f32_16x16x32_bf16 v[28:31], v[186:189], v[206:209], v[28:31]
	ds_read_b128 v[186:189], v212 offset:17920
	v_mfma_f32_16x16x32_bf16 v[24:27], v[190:193], v[206:209], v[24:27]
	ds_read_b128 v[190:193], v212 offset:19200
	s_waitcnt lgkmcnt(1)
	v_mfma_f32_16x16x32_bf16 v[120:123], v[186:189], v[194:197], v[120:123]
	s_waitcnt lgkmcnt(0)
	v_mfma_f32_16x16x32_bf16 v[112:115], v[190:193], v[194:197], v[112:115]
	v_mfma_f32_16x16x32_bf16 v[88:91], v[186:189], v[198:201], v[88:91]
	v_mfma_f32_16x16x32_bf16 v[80:83], v[190:193], v[198:201], v[80:83]
	v_mfma_f32_16x16x32_bf16 v[56:59], v[186:189], v[202:205], v[56:59]
	v_mfma_f32_16x16x32_bf16 v[44:47], v[190:193], v[202:205], v[44:47]
	v_mfma_f32_16x16x32_bf16 v[20:23], v[186:189], v[206:209], v[20:23]
	v_mfma_f32_16x16x32_bf16 v[12:15], v[190:193], v[206:209], v[12:15]
	s_setprio 0
	v_lshl_add_u64 v[172:173], v[172:173], 0, s[26:27]
	s_cmp_eq_u32 s12, 30
	v_lshl_add_u64 v[174:175], v[174:175], 0, s[38:39]
	s_barrier
	s_cbranch_scc0 .LBB0_126
; #define G_LOAD(kt_) do { \
;     if constexpr (AF32) { _Pragma("unroll") for (int i = 0; i < 4; ++i) ld16_sc1(ra[i], Af + (size_t)i * 32 * lda + (kt_) * 32); } \
;     else { _Pragma("unroll") for (int i = 0; i < 2; ++i) ld16_sc1(rab[i], Ab + (size_t)i * 64 * lda + (kt_) * 32); } \
;     _Pragma("unroll") for (int i = 0; i < 4; ++i) ld16_sc1(rb[i], Bp + (size_t)(kt_) * bstep + i * 2048); } while (0)
; template <bool AF32, class Epi>
; __device__ __forceinline__ void gemm_tile(unsigned char* smem, const void* Ap, int lda, const bf16_t* WT, int N, int K, const Epi& epi, int m0, int n0,
;                                           GPre& pr, bool preloaded, const void* nAp, int nn0, bool has_next) {
;     ...
;   for (int kt = 0; kt < nk; ++kt) {
;     const int cur = kt & 1;
;     if (kt + 1 < nk) G_STORE(cur ^ 1);
;     if (kt + 2 < nk) G_LOAD(kt + 2);
;     const bf16_t* a_s = sbase + cur * G_STAGE + (wr * 64 + l15) * GLD + quad * 8;
;     const bf16_t* b_s = sbase + cur * G_STAGE + 128 * GLD + (wc * 128 + l15) * GLD + quad * 8;
;     __builtin_amdgcn_s_setprio(1);
;     bf16x8 af[4];
; #pragma unroll
;     for (int m = 0; m < 4; ++m) af[m] = *(const bf16x8*)(a_s + m * 16 * GLD);
; #pragma unroll
;     for (int nh = 0; nh < 4; ++nh) {
;       bf16x8 bfr[2];
; #pragma unroll
;       for (int n2 = 0; n2 < 2; ++n2) bfr[n2] = *(const bf16x8*)(b_s + (nh * 2 + n2) * 16 * GLD);
; #pragma unroll
;       for (int m = 0; m < 4; ++m)
; #pragma unroll
;         for (int n2 = 0; n2 < 2; ++n2) acc[m][nh * 2 + n2] = __builtin_amdgcn_mfma_f32_16x16x32_bf16(bfr[n2], af[m], acc[m][nh * 2 + n2], 0, 0, 0);
;     }
;     __builtin_amdgcn_s_setprio(0);
;     __syncthreads();
	s_waitcnt vmcnt(0)
	s_nop 0
	v_cvt_pk_bf16_f32 v172, v16, v17
	v_mul_f32_e32 v17, v17, v17
	v_fmac_f32_e32 v17, v16, v16
	v_cvt_pk_bf16_f32 v173, v18, v19
	v_cvt_pk_bf16_f32 v174, v8, v9
	v_cvt_pk_bf16_f32 v175, v10, v11
	v_fmac_f32_e32 v17, v18, v18
	ds_write2st64_b64 v171, v[172:173], v[174:175] offset0:60 offset1:65
	v_cvt_pk_bf16_f32 v172, v4, v5
	v_cvt_pk_bf16_f32 v173, v6, v7
	v_cvt_pk_bf16_f32 v174, v0, v1
	v_cvt_pk_bf16_f32 v175, v2, v3
	v_fmac_f32_e32 v17, v19, v19
	ds_write2st64_b64 v171, v[172:173], v[174:175] offset0:70 offset1:75
	ds_write_b128 v182, v[32:35] offset:40960
	ds_write_b128 v182, v[36:39] offset:46080
	ds_write_b128 v182, v[40:43] offset:51200
	ds_write_b128 v182, v[48:51] offset:56320
	v_add_f32_e32 v169, v169, v17
	v_add_u32_e32 v174, v166, v184
	s_setprio 1
	v_add_u32_e32 v175, v183, v184
	ds_read_b128 v[16:19], v175 offset:10240
	ds_read_b128 v[32:35], v175 offset:11520
	ds_read_b128 v[36:39], v174
	ds_read_b128 v[40:43], v174 offset:1280
	s_waitcnt lgkmcnt(1)
	v_mfma_f32_16x16x32_bf16 v[48:51], v[16:19], v[36:39], v[156:159]
	s_waitcnt lgkmcnt(0)
	v_mfma_f32_16x16x32_bf16 v[156:159], v[32:35], v[40:43], v[136:139]
	s_nop 2
	ds_read_b128 v[136:139], v174 offset:2560
	ds_read_b128 v[170:173], v174 offset:3840
	v_mfma_f32_16x16x32_bf16 v[152:155], v[32:35], v[36:39], v[152:155]
	v_mfma_f32_16x16x32_bf16 v[140:143], v[16:19], v[40:43], v[140:143]
	s_waitcnt lgkmcnt(1)
	v_mfma_f32_16x16x32_bf16 v[108:111], v[16:19], v[136:139], v[108:111]
	v_mfma_f32_16x16x32_bf16 v[100:103], v[32:35], v[136:139], v[100:103]
	s_waitcnt lgkmcnt(0)
	v_mfma_f32_16x16x32_bf16 v[16:19], v[16:19], v[170:173], v[76:79]
	s_nop 2
	ds_read_b128 v[76:79], v175 offset:12800
	v_mfma_f32_16x16x32_bf16 v[32:35], v[32:35], v[170:173], v[68:71]
	s_nop 2
	ds_read_b128 v[68:71], v175 offset:14080
	s_waitcnt lgkmcnt(1)
	v_mfma_f32_16x16x32_bf16 v[148:151], v[76:79], v[36:39], v[148:151]
	s_waitcnt lgkmcnt(0)
	v_mfma_f32_16x16x32_bf16 v[144:147], v[68:71], v[36:39], v[144:147]
	v_mfma_f32_16x16x32_bf16 v[124:127], v[76:79], v[40:43], v[124:127]
	v_mfma_f32_16x16x32_bf16 v[116:119], v[68:71], v[40:43], v[116:119]
	v_mfma_f32_16x16x32_bf16 v[92:95], v[76:79], v[136:139], v[92:95]
	v_mfma_f32_16x16x32_bf16 v[84:87], v[68:71], v[136:139], v[84:87]
	v_mfma_f32_16x16x32_bf16 v[60:63], v[76:79], v[170:173], v[60:63]
	ds_read_b128 v[76:79], v175 offset:15360
	v_mfma_f32_16x16x32_bf16 v[52:55], v[68:71], v[170:173], v[52:55]
	ds_read_b128 v[68:71], v175 offset:16640
	s_waitcnt lgkmcnt(1)
	v_mfma_f32_16x16x32_bf16 v[182:185], v[76:79], v[36:39], v[132:135]
	v_mfma_f32_16x16x32_bf16 v[190:193], v[76:79], v[40:43], v[104:107]
	v_mfma_f32_16x16x32_bf16 v[198:201], v[76:79], v[136:139], v[72:75]
	v_mfma_f32_16x16x32_bf16 v[76:79], v[76:79], v[170:173], v[28:31]
	s_nop 2
	ds_read_b128 v[28:31], v175 offset:17920
	s_waitcnt lgkmcnt(1)
	v_mfma_f32_16x16x32_bf16 v[206:209], v[68:71], v[170:173], v[24:27]
	s_nop 2
	ds_read_b128 v[24:27], v175 offset:19200
	s_waitcnt lgkmcnt(0)
	v_mfma_f32_16x16x32_bf16 v[44:47], v[24:27], v[136:139], v[44:47]
	v_mfma_f32_16x16x32_bf16 v[12:15], v[24:27], v[170:173], v[12:15]
	v_mfma_f32_16x16x32_bf16 v[186:189], v[68:71], v[36:39], v[128:131]
	v_mfma_f32_16x16x32_bf16 v[194:197], v[68:71], v[40:43], v[96:99]
	v_mfma_f32_16x16x32_bf16 v[202:205], v[68:71], v[136:139], v[64:67]
	v_mfma_f32_16x16x32_bf16 v[212:215], v[28:31], v[36:39], v[120:123]
	v_mfma_f32_16x16x32_bf16 v[216:219], v[24:27], v[36:39], v[112:115]
	v_mfma_f32_16x16x32_bf16 v[220:223], v[28:31], v[40:43], v[88:91]
	v_mfma_f32_16x16x32_bf16 v[224:227], v[24:27], v[40:43], v[80:83]
	v_mfma_f32_16x16x32_bf16 v[228:231], v[28:31], v[136:139], v[56:59]
	v_mfma_f32_16x16x32_bf16 v[232:235], v[28:31], v[170:173], v[20:23]
	s_setprio 0
	s_barrier
; #define G_LOAD(kt_) do { \
;     if constexpr (AF32) { _Pragma("unroll") for (int i = 0; i < 4; ++i) ld16_sc1(ra[i], Af + (size_t)i * 32 * lda + (kt_) * 32); } \
;     else { _Pragma("unroll") for (int i = 0; i < 2; ++i) ld16_sc1(rab[i], Ab + (size_t)i * 64 * lda + (kt_) * 32); } \
;     _Pragma("unroll") for (int i = 0; i < 4; ++i) ld16_sc1(rb[i], Bp + (size_t)(kt_) * bstep + i * 2048); } while (0)
; template <bool AF32, class Epi>
; __device__ __forceinline__ void gemm_tile(unsigned char* smem, const void* Ap, int lda, const bf16_t* WT, int N, int K, const Epi& epi, int m0, int n0,
;                                           GPre& pr, bool preloaded, const void* nAp, int nn0, bool has_next) {
;     ...
;     for (int nh = 0; nh < 4; ++nh) {
;       bf16x8 bfr[2];
; #pragma unroll
;       for (int n2 = 0; n2 < 2; ++n2) bfr[n2] = *(const bf16x8*)(b_s + (nh * 2 + n2) * 16 * GLD);
; #pragma unroll
;       for (int m = 0; m < 4; ++m)
; #pragma unroll
;         for (int n2 = 0; n2 < 2; ++n2) acc[m][nh * 2 + n2] = __builtin_amdgcn_mfma_f32_16x16x32_bf16(bfr[n2], af[m], acc[m][nh * 2 + n2], 0, 0, 0);
;     }
;     __builtin_amdgcn_s_setprio(0);
;     __syncthreads();
;   }
;   if (has_next) {
;     const float* Af = (const float*)nAp + (size_t)(tid >> 3) * lda + (tid & 7) * 4;
;     const bf16_t* Ab = (const bf16_t*)nAp + (size_t)(tid >> 2) * lda + (tid & 3) * 8;
;     const bf16_t* Bp = WT + (size_t)nn0 * 32 + tid * 8;
;     G_LOAD(0);
;   }
;     ...
;   if constexpr (AF32) {
;     const float invK = 1.0f / (float)K;
; #pragma unroll
;     for (int i = 0; i < 4; ++i) {
;       float s = ss[i];
;       s += __shfl_xor(s, 1); s += __shfl_xor(s, 2); s += __shfl_xor(s, 4);
;       if ((tid & 7) == 0) sR[(tid >> 3) + 32 * i] = rsqrtf(s * invK + EPS);
;     }
;     __syncthreads();
	s_setprio 1
	ds_read_b128 v[20:23], v175 offset:40960
	ds_read_b128 v[24:27], v175 offset:42240
	ds_read_b128 v[170:173], v174 offset:30720
	ds_read_b128 v[236:239], v174 offset:32000
	s_waitcnt lgkmcnt(1)
	v_mfma_f32_16x16x32_bf16 v[128:131], v[24:27], v[170:173], v[152:155]
	s_waitcnt lgkmcnt(0)
	v_mfma_f32_16x16x32_bf16 v[104:107], v[20:23], v[236:239], v[140:143]
	s_nop 2
	ds_read_b128 v[140:143], v174 offset:33280
	ds_read_b128 v[152:155], v174 offset:34560
	s_waitcnt lgkmcnt(0)
	v_mfma_f32_16x16x32_bf16 v[40:43], v[20:23], v[152:155], v[16:19]
	s_nop 2
	ds_read_b128 v[16:19], v175 offset:43520
	v_mfma_f32_16x16x32_bf16 v[136:139], v[20:23], v[170:173], v[48:51]
	v_mfma_f32_16x16x32_bf16 v[72:75], v[20:23], v[140:143], v[108:111]
	ds_read_b128 v[20:23], v175 offset:44800
	v_mfma_f32_16x16x32_bf16 v[64:67], v[24:27], v[140:143], v[100:103]
	v_mfma_f32_16x16x32_bf16 v[36:39], v[24:27], v[152:155], v[32:35]
	s_waitcnt lgkmcnt(1)
	v_mfma_f32_16x16x32_bf16 v[132:135], v[16:19], v[170:173], v[148:151]
	v_mfma_f32_16x16x32_bf16 v[100:103], v[16:19], v[236:239], v[124:127]
	v_mfma_f32_16x16x32_bf16 v[68:71], v[16:19], v[140:143], v[92:95]
	v_mfma_f32_16x16x32_bf16 v[32:35], v[16:19], v[152:155], v[60:63]
	ds_read_b128 v[16:19], v175 offset:46080
	v_mfma_f32_16x16x32_bf16 v[96:99], v[24:27], v[236:239], v[156:159]
	s_waitcnt lgkmcnt(1)
	v_mfma_f32_16x16x32_bf16 v[120:123], v[20:23], v[170:173], v[144:147]
	v_mfma_f32_16x16x32_bf16 v[88:91], v[20:23], v[236:239], v[116:119]
	s_nop 1
	ds_read_b128 v[144:147], v175 offset:49920
	v_mfma_f32_16x16x32_bf16 v[56:59], v[20:23], v[140:143], v[84:87]
	v_mfma_f32_16x16x32_bf16 v[28:31], v[20:23], v[152:155], v[52:55]
	ds_read_b128 v[20:23], v175 offset:47360
	s_waitcnt lgkmcnt(2)
	v_mfma_f32_16x16x32_bf16 v[124:127], v[16:19], v[170:173], v[182:185]
	v_mfma_f32_16x16x32_bf16 v[92:95], v[16:19], v[236:239], v[190:193]
	v_mfma_f32_16x16x32_bf16 v[60:63], v[16:19], v[140:143], v[198:201]
	v_mfma_f32_16x16x32_bf16 v[24:27], v[16:19], v[152:155], v[76:79]
	ds_read_b128 v[16:19], v175 offset:48640
	s_waitcnt lgkmcnt(1)
	v_mfma_f32_16x16x32_bf16 v[112:115], v[20:23], v[170:173], v[186:189]
	v_mfma_f32_16x16x32_bf16 v[80:83], v[20:23], v[236:239], v[194:197]
	v_mfma_f32_16x16x32_bf16 v[48:51], v[20:23], v[140:143], v[202:205]
	v_mfma_f32_16x16x32_bf16 v[20:23], v[20:23], v[152:155], v[206:209]
	s_waitcnt lgkmcnt(0)
	v_mfma_f32_16x16x32_bf16 v[116:119], v[16:19], v[170:173], v[212:215]
	v_mfma_f32_16x16x32_bf16 v[108:111], v[144:147], v[170:173], v[216:219]
	v_mfma_f32_16x16x32_bf16 v[84:87], v[16:19], v[236:239], v[220:223]
	v_mfma_f32_16x16x32_bf16 v[76:79], v[144:147], v[236:239], v[224:227]
	v_mfma_f32_16x16x32_bf16 v[52:55], v[16:19], v[140:143], v[228:231]
	v_mfma_f32_16x16x32_bf16 v[44:47], v[144:147], v[140:143], v[44:47]
	v_mfma_f32_16x16x32_bf16 v[16:19], v[16:19], v[152:155], v[232:235]
	v_mfma_f32_16x16x32_bf16 v[12:15], v[144:147], v[152:155], v[12:15]
	s_setprio 0
	v_and_b32_e32 v141, 64, v177
	v_xor_b32_e32 v140, 1, v177
	v_add_u32_e32 v141, 64, v141
	v_cmp_lt_i32_e32 vcc, v140, v141
	v_xor_b32_e32 v142, 2, v177
	s_nop 0
	v_cndmask_b32_e32 v140, v177, v140, vcc
	v_lshlrev_b32_e32 v140, 2, v140
	ds_bpermute_b32 v143, v140, v169
	v_cmp_lt_i32_e32 vcc, v142, v141
	s_barrier
	s_waitcnt lgkmcnt(0)
	v_cndmask_b32_e32 v142, v177, v142, vcc
	v_lshlrev_b32_e32 v142, 2, v142
	v_add_f32_e32 v144, v169, v143
	ds_bpermute_b32 v145, v142, v144
	v_xor_b32_e32 v143, 4, v177
	v_cmp_lt_i32_e32 vcc, v143, v141
	s_waitcnt lgkmcnt(0)
	v_add_f32_e32 v144, v144, v145
	v_cndmask_b32_e32 v141, v177, v143, vcc
	v_lshlrev_b32_e32 v143, 2, v141
	ds_bpermute_b32 v145, v143, v144
	v_cmp_eq_u32_e32 vcc, 0, v163
	v_lshlrev_b32_e32 v141, 2, v162
	s_and_saveexec_b64 s[6:7], vcc
	s_cbranch_execz .LBB0_129
	s_waitcnt lgkmcnt(0)
	v_add_f32_e32 v144, v144, v145
	v_fmamk_f32 v144, v144, 0x3a800000, v176
	v_mul_f32_e32 v145, 0x4b800000, v144
	v_cmp_gt_f32_e64 s[4:5], s73, v144
	s_nop 1
	v_cndmask_b32_e64 v144, v144, v145, s[4:5]
	v_rsq_f32_e32 v144, v144
	s_nop 0
	v_mul_f32_e32 v145, 0x45800000, v144
	v_cndmask_b32_e64 v144, v144, v145, s[4:5]
	ds_write_b32 v141, v144 offset:61440

; #define G_LOAD(kt_) do { \
;     if constexpr (AF32) { _Pragma("unroll") for (int i = 0; i < 4; ++i) ld16_sc1(ra[i], Af + (size_t)i * 32 * lda + (kt_) * 32); } \
;     else { _Pragma("unroll") for (int i = 0; i < 2; ++i) ld16_sc1(rab[i], Ab + (size_t)i * 64 * lda + (kt_) * 32); } \
;     _Pragma("unroll") for (int i = 0; i < 4; ++i) ld16_sc1(rb[i], Bp + (size_t)(kt_) * bstep + i * 2048); } while (0)
; template <bool AF32, class Epi>
; __device__ __forceinline__ void gemm_tile(unsigned char* smem, const void* Ap, int lda, const bf16_t* WT, int N, int K, const Epi& epi, int m0, int n0,
;                                           GPre& pr, bool preloaded, const void* nAp, int nn0, bool has_next) {
;     ...
;   if (!preloaded) G_LOAD(0);
;   G_STORE(0);
;   if (nk > 1) G_LOAD(1);
;   __syncthreads();
;   for (int kt = 0; kt < nk; ++kt) {
;     const int cur = kt & 1;
;     if (kt + 1 < nk) G_STORE(cur ^ 1);
;     if (kt + 2 < nk) G_LOAD(kt + 2);
;     const bf16_t* a_s = sbase + cur * G_STAGE + (wr * 64 + l15) * GLD + quad * 8;
;     const bf16_t* b_s = sbase + cur * G_STAGE + 128 * GLD + (wc * 128 + l15) * GLD + quad * 8;
;     __builtin_amdgcn_s_setprio(1);
;     bf16x8 af[4];
; #pragma unroll
;     for (int m = 0; m < 4; ++m) af[m] = *(const bf16x8*)(a_s + m * 16 * GLD);
; #pragma unroll
;     for (int nh = 0; nh < 4; ++nh) {
;       bf16x8 bfr[2];
; #pragma unroll
;       for (int n2 = 0; n2 < 2; ++n2) bfr[n2] = *(const bf16x8*)(b_s + (nh * 2 + n2) * 16 * GLD);
; #pragma unroll
;       for (int m = 0; m < 4; ++m)
; #pragma unroll
;         for (int n2 = 0; n2 < 2; ++n2) acc[m][nh * 2 + n2] = __builtin_amdgcn_mfma_f32_16x16x32_bf16(bfr[n2], af[m], acc[m][nh * 2 + n2], 0, 0, 0);
;     }
;     __builtin_amdgcn_s_setprio(0);
;     __syncthreads();
;   }
.LBB0_141:
	s_and_b32 s3, s4, 1
	s_waitcnt vmcnt(0)
	s_xor_b32 s5, s3, 1
	v_cvt_pk_bf16_f32 v198, v4, v5
	v_mov_b32_e32 v201, v4
	v_mov_b32_e32 v4, v137
	s_mulk_i32 s5, 0x7800
	v_lshl_add_u32 v209, v170, 1, s5
	ds_write_b128 v209, v[20:23] offset:10240
	ds_write_b128 v209, v[24:27] offset:15360
	ds_write_b128 v209, v[28:31] offset:20480
	ds_write_b128 v209, v[36:39] offset:25600
	s_setprio 2
	global_load_dwordx4 v[20:23], v[172:173], off sc1
	v_lshl_add_u64 v[192:193], v[172:173], 0, s[30:31]
	global_load_dwordx4 v[24:27], v[192:193], off sc1
	v_lshl_add_u64 v[194:195], v[172:173], 0, s[34:35]
	global_load_dwordx4 v[28:31], v[194:195], off sc1
	v_lshl_add_u64 v[196:197], v[172:173], 0, s[36:37]
	global_load_dwordx4 v[36:39], v[196:197], off sc1
	s_setprio 0
	v_mov_b32_e32 v200, v136
	v_pk_mul_f32 v[4:5], v[4:5], v[4:5]
	v_lshl_add_u32 v208, v184, 1, s5
	v_cvt_pk_bf16_f32 v199, v6, v7
	v_mov_b32_e32 v202, v138
	v_mov_b32_e32 v203, v6
	v_mov_b32_e32 v6, v139
	v_cvt_pk_bf16_f32 v136, v136, v137
	v_cvt_pk_bf16_f32 v137, v138, v139
	v_cvt_pk_bf16_f32 v138, v132, v133
	v_cvt_pk_bf16_f32 v139, v134, v135
	v_mov_b32_e32 v204, v128
	v_mov_b32_e32 v205, v132
	v_mov_b32_e32 v132, v129
	v_cvt_pk_bf16_f32 v128, v128, v129
	v_cvt_pk_bf16_f32 v129, v130, v131
	v_pk_fma_f32 v[4:5], v[200:201], v[200:201], v[4:5]
	v_mov_b32_e32 v206, v130
	v_mov_b32_e32 v207, v134
	v_mov_b32_e32 v134, v131
	ds_write2st64_b64 v208, v[198:199], v[136:137] offset1:5
	v_pk_mul_f32 v[130:131], v[132:133], v[132:133]
	ds_write2st64_b64 v208, v[138:139], v[128:129] offset0:10 offset1:15
	v_pk_fma_f32 v[4:5], v[202:203], v[202:203], v[4:5]
	v_pk_fma_f32 v[216:217], v[204:205], v[204:205], v[130:131]
	v_pk_fma_f32 v[198:199], v[6:7], v[6:7], v[4:5]
	s_setprio 2
	global_load_dwordx4 v[4:7], v[174:175], off sc1
	v_lshl_add_u64 v[186:187], v[174:175], 0, s[26:27]
	v_pk_fma_f32 v[216:217], v[206:207], v[206:207], v[216:217]
	global_load_dwordx4 v[136:139], v[186:187], off sc1
	v_lshl_add_u64 v[188:189], v[174:175], 0, s[28:29]
	v_pk_fma_f32 v[200:201], v[134:135], v[134:135], v[216:217]
	global_load_dwordx4 v[132:135], v[188:189], off sc1
	v_lshl_add_u64 v[190:191], v[174:175], 0, s[22:23]
	global_load_dwordx4 v[128:131], v[190:191], off sc1
	s_setprio 0
	s_add_i32 s4, s4, 1
	s_mulk_i32 s3, 0x7800
	v_pk_add_f32 v[168:169], v[168:169], v[198:199]
	v_pk_add_f32 v[166:167], v[166:167], v[200:201]
	v_add3_u32 v206, s3, v162, v160
	s_setprio 1
	v_add3_u32 v212, s3, v185, v160
	ds_read_b128 v[186:189], v212 offset:10240
	ds_read_b128 v[190:193], v212 offset:11520
	ds_read_b128 v[194:197], v206
	ds_read_b128 v[198:201], v206 offset:1280
	ds_read_b128 v[202:205], v206 offset:2560
	ds_read_b128 v[206:209], v206 offset:3840
	s_waitcnt lgkmcnt(3)
	v_mfma_f32_16x16x32_bf16 v[156:159], v[186:189], v[194:197], v[156:159]
	v_mfma_f32_16x16x32_bf16 v[152:155], v[190:193], v[194:197], v[152:155]
	s_waitcnt lgkmcnt(2)
	v_mfma_f32_16x16x32_bf16 v[140:143], v[186:189], v[198:201], v[140:143]
	v_mfma_f32_16x16x32_bf16 v[124:127], v[190:193], v[198:201], v[124:127]
	s_waitcnt lgkmcnt(1)
	v_mfma_f32_16x16x32_bf16 v[96:99], v[186:189], v[202:205], v[96:99]
	v_mfma_f32_16x16x32_bf16 v[88:91], v[190:193], v[202:205], v[88:91]
	s_waitcnt lgkmcnt(0)
	v_mfma_f32_16x16x32_bf16 v[64:67], v[186:189], v[206:209], v[64:67]
	ds_read_b128 v[186:189], v212 offset:12800
	v_mfma_f32_16x16x32_bf16 v[56:59], v[190:193], v[206:209], v[56:59]
	ds_read_b128 v[190:193], v212 offset:14080
	s_waitcnt lgkmcnt(1)
	v_mfma_f32_16x16x32_bf16 v[148:151], v[186:189], v[194:197], v[148:151]
	s_waitcnt lgkmcnt(0)
	v_mfma_f32_16x16x32_bf16 v[144:147], v[190:193], v[194:197], v[144:147]
	v_mfma_f32_16x16x32_bf16 v[112:115], v[186:189], v[198:201], v[112:115]
	v_mfma_f32_16x16x32_bf16 v[104:107], v[190:193], v[198:201], v[104:107]
	v_mfma_f32_16x16x32_bf16 v[80:83], v[186:189], v[202:205], v[80:83]
	v_mfma_f32_16x16x32_bf16 v[72:75], v[190:193], v[202:205], v[72:75]
	v_mfma_f32_16x16x32_bf16 v[48:51], v[186:189], v[206:209], v[48:51]
	ds_read_b128 v[186:189], v212 offset:15360
	v_mfma_f32_16x16x32_bf16 v[40:43], v[190:193], v[206:209], v[40:43]
	ds_read_b128 v[190:193], v212 offset:16640
	s_waitcnt lgkmcnt(1)
	v_mfma_f32_16x16x32_bf16 v[120:123], v[186:189], v[194:197], v[120:123]
	s_waitcnt lgkmcnt(0)
	v_mfma_f32_16x16x32_bf16 v[116:119], v[190:193], v[194:197], v[116:119]
	v_mfma_f32_16x16x32_bf16 v[92:95], v[186:189], v[198:201], v[92:95]
	v_mfma_f32_16x16x32_bf16 v[84:87], v[190:193], v[198:201], v[84:87]
	v_mfma_f32_16x16x32_bf16 v[60:63], v[186:189], v[202:205], v[60:63]
	v_mfma_f32_16x16x32_bf16 v[52:55], v[190:193], v[202:205], v[52:55]
	v_mfma_f32_16x16x32_bf16 v[16:19], v[186:189], v[206:209], v[16:19]
	ds_read_b128 v[186:189], v212 offset:17920
	v_mfma_f32_16x16x32_bf16 v[12:15], v[190:193], v[206:209], v[12:15]
	ds_read_b128 v[190:193], v212 offset:19200
	s_waitcnt lgkmcnt(1)
	v_mfma_f32_16x16x32_bf16 v[108:111], v[186:189], v[194:197], v[108:111]
	s_waitcnt lgkmcnt(0)
	v_mfma_f32_16x16x32_bf16 v[100:103], v[190:193], v[194:197], v[100:103]
	v_mfma_f32_16x16x32_bf16 v[76:79], v[186:189], v[198:201], v[76:79]
	v_mfma_f32_16x16x32_bf16 v[68:71], v[190:193], v[198:201], v[68:71]
	v_mfma_f32_16x16x32_bf16 v[44:47], v[186:189], v[202:205], v[44:47]
	v_mfma_f32_16x16x32_bf16 v[32:35], v[190:193], v[202:205], v[32:35]
	v_mfma_f32_16x16x32_bf16 v[8:11], v[186:189], v[206:209], v[8:11]
	v_mfma_f32_16x16x32_bf16 v[0:3], v[190:193], v[206:209], v[0:3]
	s_setprio 0
	v_lshl_add_u64 v[172:173], v[172:173], 0, s[56:57]
	s_cmp_eq_u32 s4, 30
	v_lshl_add_u64 v[174:175], v[174:175], 0, s[38:39]
	s_barrier
	s_cbranch_scc0 .LBB0_141
; #define G_LOAD(kt_) do { \
;     if constexpr (AF32) { _Pragma("unroll") for (int i = 0; i < 4; ++i) ld16_sc1(ra[i], Af + (size_t)i * 32 * lda + (kt_) * 32); } \
;     else { _Pragma("unroll") for (int i = 0; i < 2; ++i) ld16_sc1(rab[i], Ab + (size_t)i * 64 * lda + (kt_) * 32); } \
;     _Pragma("unroll") for (int i = 0; i < 4; ++i) ld16_sc1(rb[i], Bp + (size_t)(kt_) * bstep + i * 2048); } while (0)
; template <bool AF32, class Epi>
; __device__ __forceinline__ void gemm_tile(unsigned char* smem, const void* Ap, int lda, const bf16_t* WT, int N, int K, const Epi& epi, int m0, int n0,
;                                           GPre& pr, bool preloaded, const void* nAp, int nn0, bool has_next) {
;     ...
;   for (int kt = 0; kt < nk; ++kt) {
;     const int cur = kt & 1;
;     if (kt + 1 < nk) G_STORE(cur ^ 1);
;     if (kt + 2 < nk) G_LOAD(kt + 2);
;     const bf16_t* a_s = sbase + cur * G_STAGE + (wr * 64 + l15) * GLD + quad * 8;
;     const bf16_t* b_s = sbase + cur * G_STAGE + 128 * GLD + (wc * 128 + l15) * GLD + quad * 8;
;     __builtin_amdgcn_s_setprio(1);
;     bf16x8 af[4];
; #pragma unroll
;     for (int m = 0; m < 4; ++m) af[m] = *(const bf16x8*)(a_s + m * 16 * GLD);
; #pragma unroll
;     for (int nh = 0; nh < 4; ++nh) {
;       bf16x8 bfr[2];
; #pragma unroll
;       for (int n2 = 0; n2 < 2; ++n2) bfr[n2] = *(const bf16x8*)(b_s + (nh * 2 + n2) * 16 * GLD);
; #pragma unroll
;       for (int m = 0; m < 4; ++m)
; #pragma unroll
;         for (int n2 = 0; n2 < 2; ++n2) acc[m][nh * 2 + n2] = __builtin_amdgcn_mfma_f32_16x16x32_bf16(bfr[n2], af[m], acc[m][nh * 2 + n2], 0, 0, 0);
;     }
;     __builtin_amdgcn_s_setprio(0);
;     __syncthreads();
	s_waitcnt vmcnt(0)
	s_nop 0
	v_cvt_pk_bf16_f32 v172, v4, v5
	v_mul_f32_e32 v5, v5, v5
	v_fmac_f32_e32 v5, v4, v4
	v_cvt_pk_bf16_f32 v173, v6, v7
	v_cvt_pk_bf16_f32 v174, v136, v137
	v_cvt_pk_bf16_f32 v175, v138, v139
	v_fmac_f32_e32 v5, v6, v6
	ds_write2st64_b64 v183, v[172:173], v[174:175] offset0:60 offset1:65
	v_cvt_pk_bf16_f32 v172, v132, v133
	v_cvt_pk_bf16_f32 v173, v134, v135
	v_cvt_pk_bf16_f32 v174, v128, v129
	v_cvt_pk_bf16_f32 v175, v130, v131
	v_fmac_f32_e32 v5, v7, v7
	ds_write2st64_b64 v183, v[172:173], v[174:175] offset0:70 offset1:75
	ds_write_b128 v171, v[20:23] offset:40960
	ds_write_b128 v171, v[24:27] offset:46080
	ds_write_b128 v171, v[28:31] offset:51200
	ds_write_b128 v171, v[36:39] offset:56320
	v_add_f32_e32 v169, v169, v5
	v_add_u32_e32 v174, v162, v160
	s_setprio 1
	v_add_u32_e32 v160, v185, v160
	ds_read_b128 v[4:7], v160 offset:10240
	ds_read_b128 v[20:23], v160 offset:11520
	ds_read_b128 v[24:27], v174
	ds_read_b128 v[28:31], v174 offset:1280
	s_waitcnt lgkmcnt(1)
	v_mfma_f32_16x16x32_bf16 v[36:39], v[4:7], v[24:27], v[156:159]
	s_waitcnt lgkmcnt(0)
	v_mfma_f32_16x16x32_bf16 v[156:159], v[20:23], v[28:31], v[124:127]
	s_nop 2
	ds_read_b128 v[124:127], v174 offset:2560
	ds_read_b128 v[170:173], v174 offset:3840
	v_mfma_f32_16x16x32_bf16 v[152:155], v[20:23], v[24:27], v[152:155]
	v_mfma_f32_16x16x32_bf16 v[140:143], v[4:7], v[28:31], v[140:143]
	s_waitcnt lgkmcnt(1)
	v_mfma_f32_16x16x32_bf16 v[96:99], v[4:7], v[124:127], v[96:99]
	v_mfma_f32_16x16x32_bf16 v[88:91], v[20:23], v[124:127], v[88:91]
	s_waitcnt lgkmcnt(0)
	v_mfma_f32_16x16x32_bf16 v[4:7], v[4:7], v[170:173], v[64:67]
	s_nop 2
	ds_read_b128 v[64:67], v160 offset:12800
	v_mfma_f32_16x16x32_bf16 v[20:23], v[20:23], v[170:173], v[56:59]
	s_nop 2
	ds_read_b128 v[56:59], v160 offset:14080
	s_waitcnt lgkmcnt(1)
	v_mfma_f32_16x16x32_bf16 v[148:151], v[64:67], v[24:27], v[148:151]
	s_waitcnt lgkmcnt(0)
	v_mfma_f32_16x16x32_bf16 v[144:147], v[56:59], v[24:27], v[144:147]
	v_mfma_f32_16x16x32_bf16 v[184:187], v[64:67], v[28:31], v[112:115]
	v_mfma_f32_16x16x32_bf16 v[188:191], v[56:59], v[28:31], v[104:107]
	v_mfma_f32_16x16x32_bf16 v[80:83], v[64:67], v[124:127], v[80:83]
	v_mfma_f32_16x16x32_bf16 v[192:195], v[56:59], v[124:127], v[72:75]
	v_mfma_f32_16x16x32_bf16 v[48:51], v[64:67], v[170:173], v[48:51]
	ds_read_b128 v[64:67], v160 offset:15360
	v_mfma_f32_16x16x32_bf16 v[40:43], v[56:59], v[170:173], v[40:43]
	ds_read_b128 v[56:59], v160 offset:16640
	s_waitcnt lgkmcnt(0)
	v_mfma_f32_16x16x32_bf16 v[200:203], v[56:59], v[24:27], v[116:119]
	v_mfma_f32_16x16x32_bf16 v[212:215], v[56:59], v[28:31], v[84:87]
	v_mfma_f32_16x16x32_bf16 v[220:223], v[56:59], v[124:127], v[52:55]
	s_nop 2
	ds_read_b128 v[52:55], v160 offset:17920
	v_mfma_f32_16x16x32_bf16 v[56:59], v[56:59], v[170:173], v[12:15]
	s_nop 2
	ds_read_b128 v[12:15], v160 offset:19200
	v_mfma_f32_16x16x32_bf16 v[196:199], v[64:67], v[24:27], v[120:123]
	v_mfma_f32_16x16x32_bf16 v[16:19], v[64:67], v[170:173], v[16:19]
	s_waitcnt lgkmcnt(1)
	v_mfma_f32_16x16x32_bf16 v[224:227], v[52:55], v[24:27], v[108:111]
	s_waitcnt lgkmcnt(0)
	v_mfma_f32_16x16x32_bf16 v[24:27], v[12:15], v[24:27], v[100:103]
	v_mfma_f32_16x16x32_bf16 v[0:3], v[12:15], v[170:173], v[0:3]
	v_mfma_f32_16x16x32_bf16 v[204:207], v[64:67], v[28:31], v[92:95]
	v_mfma_f32_16x16x32_bf16 v[216:219], v[64:67], v[124:127], v[60:63]
	v_mfma_f32_16x16x32_bf16 v[228:231], v[52:55], v[28:31], v[76:79]
	v_mfma_f32_16x16x32_bf16 v[232:235], v[12:15], v[28:31], v[68:71]
	v_mfma_f32_16x16x32_bf16 v[236:239], v[52:55], v[124:127], v[44:47]
	v_mfma_f32_16x16x32_bf16 v[240:243], v[12:15], v[124:127], v[32:35]
	v_mfma_f32_16x16x32_bf16 v[244:247], v[52:55], v[170:173], v[8:11]
	s_setprio 0
	s_barrier
; #define G_LOAD(kt_) do { \
;     if constexpr (AF32) { _Pragma("unroll") for (int i = 0; i < 4; ++i) ld16_sc1(ra[i], Af + (size_t)i * 32 * lda + (kt_) * 32); } \
;     else { _Pragma("unroll") for (int i = 0; i < 2; ++i) ld16_sc1(rab[i], Ab + (size_t)i * 64 * lda + (kt_) * 32); } \
;     _Pragma("unroll") for (int i = 0; i < 4; ++i) ld16_sc1(rb[i], Bp + (size_t)(kt_) * bstep + i * 2048); } while (0)
; template <bool AF32, class Epi>
; __device__ __forceinline__ void gemm_tile(unsigned char* smem, const void* Ap, int lda, const bf16_t* WT, int N, int K, const Epi& epi, int m0, int n0,
;                                           GPre& pr, bool preloaded, const void* nAp, int nn0, bool has_next) {
;     ...
;     for (int nh = 0; nh < 4; ++nh) {
;       bf16x8 bfr[2];
; #pragma unroll
;       for (int n2 = 0; n2 < 2; ++n2) bfr[n2] = *(const bf16x8*)(b_s + (nh * 2 + n2) * 16 * GLD);
; #pragma unroll
;       for (int m = 0; m < 4; ++m)
; #pragma unroll
;         for (int n2 = 0; n2 < 2; ++n2) acc[m][nh * 2 + n2] = __builtin_amdgcn_mfma_f32_16x16x32_bf16(bfr[n2], af[m], acc[m][nh * 2 + n2], 0, 0, 0);
;     }
;     __builtin_amdgcn_s_setprio(0);
;     __syncthreads();
;   }
;   if (has_next) {
;     const float* Af = (const float*)nAp + (size_t)(tid >> 3) * lda + (tid & 7) * 4;
;     const bf16_t* Ab = (const bf16_t*)nAp + (size_t)(tid >> 2) * lda + (tid & 3) * 8;
;     const bf16_t* Bp = WT + (size_t)nn0 * 32 + tid * 8;
;     G_LOAD(0);
;   }
;     ...
;   if constexpr (AF32) {
;     const float invK = 1.0f / (float)K;
; #pragma unroll
;     for (int i = 0; i < 4; ++i) {
;       float s = ss[i];
;       s += __shfl_xor(s, 1); s += __shfl_xor(s, 2); s += __shfl_xor(s, 4);
;       if ((tid & 7) == 0) sR[(tid >> 3) + 32 * i] = rsqrtf(s * invK + EPS);
;     }
;     __syncthreads();
	s_setprio 1
	ds_read_b128 v[8:11], v160 offset:40960
	ds_read_b128 v[12:15], v160 offset:42240
	ds_read_b128 v[32:35], v174 offset:30720
	ds_read_b128 v[170:173], v174 offset:32000
	s_waitcnt lgkmcnt(1)
	v_mfma_f32_16x16x32_bf16 v[116:119], v[12:15], v[32:35], v[152:155]
	s_waitcnt lgkmcnt(0)
	v_mfma_f32_16x16x32_bf16 v[108:111], v[8:11], v[170:173], v[140:143]
	s_nop 2
	ds_read_b128 v[140:143], v174 offset:33280
	ds_read_b128 v[152:155], v174 offset:34560
	s_waitcnt lgkmcnt(0)
	v_mfma_f32_16x16x32_bf16 v[76:79], v[8:11], v[152:155], v[4:7]
	s_nop 2
	ds_read_b128 v[4:7], v160 offset:43520
	v_mfma_f32_16x16x32_bf16 v[124:127], v[8:11], v[32:35], v[36:39]
	v_mfma_f32_16x16x32_bf16 v[92:95], v[8:11], v[140:143], v[96:99]
	ds_read_b128 v[8:11], v160 offset:44800
	v_mfma_f32_16x16x32_bf16 v[84:87], v[12:15], v[140:143], v[88:91]
	s_waitcnt lgkmcnt(1)
	v_mfma_f32_16x16x32_bf16 v[120:123], v[4:7], v[32:35], v[148:151]
	v_mfma_f32_16x16x32_bf16 v[104:107], v[4:7], v[170:173], v[184:187]
	v_mfma_f32_16x16x32_bf16 v[88:91], v[4:7], v[140:143], v[80:83]
	v_mfma_f32_16x16x32_bf16 v[68:71], v[4:7], v[152:155], v[48:51]
	ds_read_b128 v[4:7], v160 offset:46080
	v_mfma_f32_16x16x32_bf16 v[100:103], v[12:15], v[170:173], v[156:159]
	v_mfma_f32_16x16x32_bf16 v[72:75], v[12:15], v[152:155], v[20:23]
	s_waitcnt lgkmcnt(1)
	v_mfma_f32_16x16x32_bf16 v[112:115], v[8:11], v[32:35], v[144:147]
	v_mfma_f32_16x16x32_bf16 v[96:99], v[8:11], v[170:173], v[188:191]
	s_nop 1
	ds_read_b128 v[144:147], v160 offset:49920
	v_mfma_f32_16x16x32_bf16 v[80:83], v[8:11], v[140:143], v[192:195]
	v_mfma_f32_16x16x32_bf16 v[64:67], v[8:11], v[152:155], v[40:43]
	ds_read_b128 v[8:11], v160 offset:47360
	s_waitcnt lgkmcnt(2)
	v_mfma_f32_16x16x32_bf16 v[60:63], v[4:7], v[32:35], v[196:199]
	v_mfma_f32_16x16x32_bf16 v[44:47], v[4:7], v[170:173], v[204:207]
	v_mfma_f32_16x16x32_bf16 v[28:31], v[4:7], v[140:143], v[216:219]
	v_mfma_f32_16x16x32_bf16 v[12:15], v[4:7], v[152:155], v[16:19]
	ds_read_b128 v[4:7], v160 offset:48640
	s_waitcnt lgkmcnt(1)
	v_mfma_f32_16x16x32_bf16 v[52:55], v[8:11], v[32:35], v[200:203]
	v_mfma_f32_16x16x32_bf16 v[36:39], v[8:11], v[170:173], v[212:215]
	v_mfma_f32_16x16x32_bf16 v[20:23], v[8:11], v[140:143], v[220:223]
	v_mfma_f32_16x16x32_bf16 v[8:11], v[8:11], v[152:155], v[56:59]
	s_waitcnt lgkmcnt(0)
	v_mfma_f32_16x16x32_bf16 v[56:59], v[4:7], v[32:35], v[224:227]
	v_mfma_f32_16x16x32_bf16 v[48:51], v[144:147], v[32:35], v[24:27]
	v_mfma_f32_16x16x32_bf16 v[40:43], v[4:7], v[170:173], v[228:231]
	v_mfma_f32_16x16x32_bf16 v[32:35], v[144:147], v[170:173], v[232:235]
	v_mfma_f32_16x16x32_bf16 v[24:27], v[4:7], v[140:143], v[236:239]
	v_mfma_f32_16x16x32_bf16 v[16:19], v[144:147], v[140:143], v[240:243]
	v_mfma_f32_16x16x32_bf16 v[4:7], v[4:7], v[152:155], v[244:247]
	v_mfma_f32_16x16x32_bf16 v[0:3], v[144:147], v[152:155], v[0:3]
	s_setprio 0
	v_and_b32_e32 v141, 64, v177
	v_xor_b32_e32 v140, 1, v177
	v_add_u32_e32 v157, 64, v141
	v_cmp_lt_i32_e32 vcc, v140, v157
	v_xor_b32_e32 v142, 2, v177
	v_xor_b32_e32 v143, 4, v177
	v_cndmask_b32_e32 v140, v177, v140, vcc
	v_lshlrev_b32_e32 v140, 2, v140
	ds_bpermute_b32 v141, v140, v169
	v_cmp_lt_i32_e32 vcc, v142, v157
	s_waitcnt lgkmcnt(0)
	s_barrier
	v_cndmask_b32_e32 v142, v177, v142, vcc
	v_lshlrev_b32_e32 v142, 2, v142
	v_add_f32_e32 v141, v169, v141
	ds_bpermute_b32 v144, v142, v141
	v_cmp_lt_i32_e32 vcc, v143, v157
	s_waitcnt lgkmcnt(0)
	v_add_f32_e32 v144, v141, v144
	v_cndmask_b32_e32 v143, v177, v143, vcc
	v_lshlrev_b32_e32 v143, 2, v143
	ds_bpermute_b32 v145, v143, v144
	v_cmp_eq_u32_e32 vcc, 0, v165
	v_lshlrev_b32_e32 v141, 2, v164
	s_and_saveexec_b64 s[6:7], vcc
	s_cbranch_execz .LBB0_144
	s_waitcnt lgkmcnt(0)
	v_add_f32_e32 v144, v144, v145
	v_fmamk_f32 v144, v144, 0x3a800000, v176
	v_mul_f32_e32 v145, 0x4b800000, v144
	v_cmp_gt_f32_e64 s[4:5], s73, v144
	s_nop 1
	v_cndmask_b32_e64 v144, v144, v145, s[4:5]
	v_rsq_f32_e32 v144, v144
	s_nop 0
	v_mul_f32_e32 v145, 0x45800000, v144
	v_cndmask_b32_e64 v144, v144, v145, s[4:5]
	ds_write_b32 v141, v144 offset:61440

; #define G_LOAD(kt_) do { \
;     if constexpr (AF32) { _Pragma("unroll") for (int i = 0; i < 4; ++i) ld16_sc1(ra[i], Af + (size_t)i * 32 * lda + (kt_) * 32); } \
;     else { _Pragma("unroll") for (int i = 0; i < 2; ++i) ld16_sc1(rab[i], Ab + (size_t)i * 64 * lda + (kt_) * 32); } \
;     _Pragma("unroll") for (int i = 0; i < 4; ++i) ld16_sc1(rb[i], Bp + (size_t)(kt_) * bstep + i * 2048); } while (0)
; template <bool AF32, class Epi>
; __device__ __forceinline__ void gemm_tile(unsigned char* smem, const void* Ap, int lda, const bf16_t* WT, int N, int K, const Epi& epi, int m0, int n0,
;                                           GPre& pr, bool preloaded, const void* nAp, int nn0, bool has_next) {
;     ...
;   if (!preloaded) G_LOAD(0);
;   G_STORE(0);
;   if (nk > 1) G_LOAD(1);
;   __syncthreads();
;   for (int kt = 0; kt < nk; ++kt) {
;     const int cur = kt & 1;
;     if (kt + 1 < nk) G_STORE(cur ^ 1);
;     if (kt + 2 < nk) G_LOAD(kt + 2);
;     const bf16_t* a_s = sbase + cur * G_STAGE + (wr * 64 + l15) * GLD + quad * 8;
;     const bf16_t* b_s = sbase + cur * G_STAGE + 128 * GLD + (wc * 128 + l15) * GLD + quad * 8;
;     __builtin_amdgcn_s_setprio(1);
;     bf16x8 af[4];
; #pragma unroll
;     for (int m = 0; m < 4; ++m) af[m] = *(const bf16x8*)(a_s + m * 16 * GLD);
; #pragma unroll
;     for (int nh = 0; nh < 4; ++nh) {
;       bf16x8 bfr[2];
; #pragma unroll
;       for (int n2 = 0; n2 < 2; ++n2) bfr[n2] = *(const bf16x8*)(b_s + (nh * 2 + n2) * 16 * GLD);
; #pragma unroll
;       for (int m = 0; m < 4; ++m)
; #pragma unroll
;         for (int n2 = 0; n2 < 2; ++n2) acc[m][nh * 2 + n2] = __builtin_amdgcn_mfma_f32_16x16x32_bf16(bfr[n2], af[m], acc[m][nh * 2 + n2], 0, 0, 0);
;     }
;     __builtin_amdgcn_s_setprio(0);
;     __syncthreads();
;   }
.LBB0_296:
	s_and_b32 s3, s49, 1
	s_waitcnt vmcnt(0)
	s_xor_b32 s51, s3, 1
	s_mulk_i32 s51, 0x7800
	v_lshl_add_u32 v176, v162, 1, s51
	ds_write_b128 v176, v[0:3] offset:10240
	ds_write_b128 v176, v[4:7] offset:15360
	ds_write_b128 v176, v[8:11] offset:20480
	ds_write_b128 v176, v[12:15] offset:25600
	s_setprio 2
	global_load_dwordx4 v[0:3], v[164:165], off sc1
	v_lshl_add_u64 v[196:197], v[164:165], 0, s[20:21]
	global_load_dwordx4 v[4:7], v[196:197], off sc1
	v_lshl_add_u64 v[198:199], v[164:165], 0, s[22:23]
	global_load_dwordx4 v[8:11], v[198:199], off sc1
	v_lshl_add_u64 v[200:201], v[164:165], 0, s[24:25]
	global_load_dwordx4 v[12:15], v[200:201], off sc1
	s_setprio 0
	v_cvt_pk_bf16_f32 v202, v28, v29
	v_mov_b32_e32 v205, v28
	v_mov_b32_e32 v28, v25
	v_lshl_add_u32 v171, v160, 1, s51
	v_cvt_pk_bf16_f32 v203, v30, v31
	v_mov_b32_e32 v204, v24
	v_mov_b32_e32 v206, v26
	v_mov_b32_e32 v207, v30
	v_mov_b32_e32 v30, v27
	v_cvt_pk_bf16_f32 v24, v24, v25
	v_cvt_pk_bf16_f32 v25, v26, v27
	v_cvt_pk_bf16_f32 v26, v20, v21
	v_cvt_pk_bf16_f32 v27, v22, v23
	v_mov_b32_e32 v208, v16
	v_mov_b32_e32 v209, v20
	v_mov_b32_e32 v20, v17
	v_mov_b32_e32 v212, v18
	v_mov_b32_e32 v213, v22
	v_mov_b32_e32 v22, v19
	v_cvt_pk_bf16_f32 v16, v16, v17
	v_cvt_pk_bf16_f32 v17, v18, v19
	v_pk_mul_f32 v[18:19], v[28:29], v[28:29]
	ds_write2st64_b64 v171, v[202:203], v[24:25] offset1:5
	ds_write2st64_b64 v171, v[26:27], v[16:17] offset0:10 offset1:15
	v_pk_fma_f32 v[216:217], v[204:205], v[204:205], v[18:19]
	v_pk_mul_f32 v[20:21], v[20:21], v[20:21]
	v_pk_fma_f32 v[216:217], v[206:207], v[206:207], v[216:217]
	v_pk_fma_f32 v[218:219], v[208:209], v[208:209], v[20:21]
	v_pk_fma_f32 v[202:203], v[30:31], v[30:31], v[216:217]
	s_setprio 2
	global_load_dwordx4 v[28:31], v[166:167], off sc1
	v_lshl_add_u64 v[172:173], v[166:167], 0, s[14:15]
	v_pk_fma_f32 v[218:219], v[212:213], v[212:213], v[218:219]
	global_load_dwordx4 v[24:27], v[172:173], off sc1
	v_lshl_add_u64 v[174:175], v[166:167], 0, s[16:17]
	v_pk_fma_f32 v[204:205], v[22:23], v[22:23], v[218:219]
	global_load_dwordx4 v[20:23], v[174:175], off sc1
	v_lshl_add_u64 v[194:195], v[166:167], 0, s[18:19]
	global_load_dwordx4 v[16:19], v[194:195], off sc1
	s_setprio 0
	s_add_i32 s49, s49, 1
	s_mulk_i32 s3, 0x7800
	v_pk_add_f32 v[186:187], v[186:187], v[202:203]
	v_pk_add_f32 v[182:183], v[182:183], v[204:205]
	v_add3_u32 v171, s3, v169, v170
	s_setprio 1
	v_add3_u32 v176, s3, v168, v170
	ds_read_b128 v[172:175], v176 offset:10240
	ds_read_b128 v[194:197], v176 offset:11520
	ds_read_b128 v[198:201], v171
	ds_read_b128 v[202:205], v171 offset:1280
	ds_read_b128 v[206:209], v171 offset:2560
	ds_read_b128 v[212:215], v171 offset:3840
	s_waitcnt lgkmcnt(3)
	v_mfma_f32_16x16x32_bf16 v[156:159], v[172:175], v[198:201], v[156:159]
	v_mfma_f32_16x16x32_bf16 v[152:155], v[194:197], v[198:201], v[152:155]
	s_waitcnt lgkmcnt(2)
	v_mfma_f32_16x16x32_bf16 v[140:143], v[172:175], v[202:205], v[140:143]
	v_mfma_f32_16x16x32_bf16 v[136:139], v[194:197], v[202:205], v[136:139]
	s_waitcnt lgkmcnt(1)
	v_mfma_f32_16x16x32_bf16 v[108:111], v[172:175], v[206:209], v[108:111]
	v_mfma_f32_16x16x32_bf16 v[100:103], v[194:197], v[206:209], v[100:103]
	s_waitcnt lgkmcnt(0)
	v_mfma_f32_16x16x32_bf16 v[76:79], v[172:175], v[212:215], v[76:79]
	ds_read_b128 v[172:175], v176 offset:12800
	v_mfma_f32_16x16x32_bf16 v[68:71], v[194:197], v[212:215], v[68:71]
	ds_read_b128 v[194:197], v176 offset:14080
	s_waitcnt lgkmcnt(1)
	v_mfma_f32_16x16x32_bf16 v[148:151], v[172:175], v[198:201], v[148:151]
	s_waitcnt lgkmcnt(0)
	v_mfma_f32_16x16x32_bf16 v[144:147], v[194:197], v[198:201], v[144:147]
	v_mfma_f32_16x16x32_bf16 v[124:127], v[172:175], v[202:205], v[124:127]
	v_mfma_f32_16x16x32_bf16 v[116:119], v[194:197], v[202:205], v[116:119]
	v_mfma_f32_16x16x32_bf16 v[92:95], v[172:175], v[206:209], v[92:95]
	v_mfma_f32_16x16x32_bf16 v[84:87], v[194:197], v[206:209], v[84:87]
	v_mfma_f32_16x16x32_bf16 v[60:63], v[172:175], v[212:215], v[60:63]
	ds_read_b128 v[172:175], v176 offset:15360
	v_mfma_f32_16x16x32_bf16 v[52:55], v[194:197], v[212:215], v[52:55]
	ds_read_b128 v[194:197], v176 offset:16640
	s_waitcnt lgkmcnt(1)
	v_mfma_f32_16x16x32_bf16 v[132:135], v[172:175], v[198:201], v[132:135]
	s_waitcnt lgkmcnt(0)
	v_mfma_f32_16x16x32_bf16 v[128:131], v[194:197], v[198:201], v[128:131]
	v_mfma_f32_16x16x32_bf16 v[104:107], v[172:175], v[202:205], v[104:107]
	v_mfma_f32_16x16x32_bf16 v[96:99], v[194:197], v[202:205], v[96:99]
	v_mfma_f32_16x16x32_bf16 v[72:75], v[172:175], v[206:209], v[72:75]
	v_mfma_f32_16x16x32_bf16 v[64:67], v[194:197], v[206:209], v[64:67]
	v_mfma_f32_16x16x32_bf16 v[44:47], v[172:175], v[212:215], v[44:47]
	ds_read_b128 v[172:175], v176 offset:17920
	v_mfma_f32_16x16x32_bf16 v[40:43], v[194:197], v[212:215], v[40:43]
	ds_read_b128 v[194:197], v176 offset:19200
	s_waitcnt lgkmcnt(1)
	v_mfma_f32_16x16x32_bf16 v[120:123], v[172:175], v[198:201], v[120:123]
	s_waitcnt lgkmcnt(0)
	v_mfma_f32_16x16x32_bf16 v[112:115], v[194:197], v[198:201], v[112:115]
	v_mfma_f32_16x16x32_bf16 v[88:91], v[172:175], v[202:205], v[88:91]
	v_mfma_f32_16x16x32_bf16 v[80:83], v[194:197], v[202:205], v[80:83]
	v_mfma_f32_16x16x32_bf16 v[56:59], v[172:175], v[206:209], v[56:59]
	v_mfma_f32_16x16x32_bf16 v[48:51], v[194:197], v[206:209], v[48:51]
	v_mfma_f32_16x16x32_bf16 v[36:39], v[172:175], v[212:215], v[36:39]
	v_mfma_f32_16x16x32_bf16 v[32:35], v[194:197], v[212:215], v[32:35]
	s_setprio 0
	v_lshl_add_u64 v[164:165], v[164:165], 0, s[36:37]
	s_cmp_eq_u32 s49, 30
	v_lshl_add_u64 v[166:167], v[166:167], 0, s[26:27]
	s_barrier
	s_cbranch_scc0 .LBB0_296
; #define G_LOAD(kt_) do { \
;     if constexpr (AF32) { _Pragma("unroll") for (int i = 0; i < 4; ++i) ld16_sc1(ra[i], Af + (size_t)i * 32 * lda + (kt_) * 32); } \
;     else { _Pragma("unroll") for (int i = 0; i < 2; ++i) ld16_sc1(rab[i], Ab + (size_t)i * 64 * lda + (kt_) * 32); } \
;     _Pragma("unroll") for (int i = 0; i < 4; ++i) ld16_sc1(rb[i], Bp + (size_t)(kt_) * bstep + i * 2048); } while (0)
; template <bool AF32, class Epi>
; __device__ __forceinline__ void gemm_tile(unsigned char* smem, const void* Ap, int lda, const bf16_t* WT, int N, int K, const Epi& epi, int m0, int n0,
;                                           GPre& pr, bool preloaded, const void* nAp, int nn0, bool has_next) {
;     ...
;   for (int kt = 0; kt < nk; ++kt) {
;     const int cur = kt & 1;
;     if (kt + 1 < nk) G_STORE(cur ^ 1);
;     if (kt + 2 < nk) G_LOAD(kt + 2);
;     const bf16_t* a_s = sbase + cur * G_STAGE + (wr * 64 + l15) * GLD + quad * 8;
;     const bf16_t* b_s = sbase + cur * G_STAGE + 128 * GLD + (wc * 128 + l15) * GLD + quad * 8;
;     __builtin_amdgcn_s_setprio(1);
;     bf16x8 af[4];
; #pragma unroll
;     for (int m = 0; m < 4; ++m) af[m] = *(const bf16x8*)(a_s + m * 16 * GLD);
; #pragma unroll
;     for (int nh = 0; nh < 4; ++nh) {
;       bf16x8 bfr[2];
; #pragma unroll
;       for (int n2 = 0; n2 < 2; ++n2) bfr[n2] = *(const bf16x8*)(b_s + (nh * 2 + n2) * 16 * GLD);
; #pragma unroll
;       for (int m = 0; m < 4; ++m)
; #pragma unroll
;         for (int n2 = 0; n2 < 2; ++n2) acc[m][nh * 2 + n2] = __builtin_amdgcn_mfma_f32_16x16x32_bf16(bfr[n2], af[m], acc[m][nh * 2 + n2], 0, 0, 0);
;     }
;     __builtin_amdgcn_s_setprio(0);
;     __syncthreads();
	s_waitcnt vmcnt(0)
	v_add_u32_e32 v176, v169, v170
	v_cvt_pk_bf16_f32 v164, v28, v29
	v_cvt_pk_bf16_f32 v165, v30, v31
	v_cvt_pk_bf16_f32 v166, v24, v25
	v_cvt_pk_bf16_f32 v167, v26, v27
	ds_write2st64_b64 v161, v[164:165], v[166:167] offset0:60 offset1:65
	v_cvt_pk_bf16_f32 v164, v20, v21
	v_cvt_pk_bf16_f32 v165, v22, v23
	v_cvt_pk_bf16_f32 v166, v16, v17
	v_cvt_pk_bf16_f32 v167, v18, v19
	ds_write2st64_b64 v161, v[164:165], v[166:167] offset0:70 offset1:75
	ds_write_b128 v163, v[0:3] offset:40960
	ds_write_b128 v163, v[4:7] offset:46080
	ds_write_b128 v163, v[8:11] offset:51200
	ds_write_b128 v163, v[12:15] offset:56320
	s_setprio 1
	v_add_u32_e32 v193, v168, v170
	ds_read_b128 v[160:163], v193 offset:10240
	ds_read_b128 v[164:167], v193 offset:11520
	ds_read_b128 v[168:171], v176
	ds_read_b128 v[172:175], v176 offset:1280
	ds_read_b128 v[194:197], v176 offset:2560
	ds_read_b128 v[198:201], v176 offset:3840
	s_waitcnt lgkmcnt(3)
	v_mfma_f32_16x16x32_bf16 v[156:159], v[160:163], v[168:171], v[156:159]
	v_mfma_f32_16x16x32_bf16 v[152:155], v[164:167], v[168:171], v[152:155]
	s_waitcnt lgkmcnt(2)
	v_mfma_f32_16x16x32_bf16 v[140:143], v[160:163], v[172:175], v[140:143]
	v_mfma_f32_16x16x32_bf16 v[136:139], v[164:167], v[172:175], v[136:139]
	s_waitcnt lgkmcnt(1)
	v_mfma_f32_16x16x32_bf16 v[108:111], v[160:163], v[194:197], v[108:111]
	v_mfma_f32_16x16x32_bf16 v[100:103], v[164:167], v[194:197], v[100:103]
	s_waitcnt lgkmcnt(0)
	v_mfma_f32_16x16x32_bf16 v[76:79], v[160:163], v[198:201], v[76:79]
	ds_read_b128 v[160:163], v193 offset:12800
	v_mfma_f32_16x16x32_bf16 v[68:71], v[164:167], v[198:201], v[68:71]
	ds_read_b128 v[164:167], v193 offset:14080
	s_waitcnt lgkmcnt(1)
	v_mfma_f32_16x16x32_bf16 v[148:151], v[160:163], v[168:171], v[148:151]
	s_waitcnt lgkmcnt(0)
	v_mfma_f32_16x16x32_bf16 v[144:147], v[164:167], v[168:171], v[144:147]
	v_mfma_f32_16x16x32_bf16 v[124:127], v[160:163], v[172:175], v[124:127]
	v_mfma_f32_16x16x32_bf16 v[116:119], v[164:167], v[172:175], v[116:119]
	v_mfma_f32_16x16x32_bf16 v[92:95], v[160:163], v[194:197], v[92:95]
	v_mfma_f32_16x16x32_bf16 v[84:87], v[164:167], v[194:197], v[84:87]
	v_mfma_f32_16x16x32_bf16 v[60:63], v[160:163], v[198:201], v[60:63]
	ds_read_b128 v[160:163], v193 offset:15360
	v_mfma_f32_16x16x32_bf16 v[52:55], v[164:167], v[198:201], v[52:55]
	ds_read_b128 v[164:167], v193 offset:16640
	s_waitcnt lgkmcnt(1)
	v_mfma_f32_16x16x32_bf16 v[212:215], v[160:163], v[194:197], v[72:75]
	s_nop 2
	ds_read_b128 v[72:75], v193 offset:19200
	s_waitcnt lgkmcnt(1)
	v_mfma_f32_16x16x32_bf16 v[216:219], v[164:167], v[194:197], v[64:67]
	s_nop 2
	ds_read_b128 v[64:67], v193 offset:17920
	v_mfma_f32_16x16x32_bf16 v[128:131], v[164:167], v[168:171], v[128:131]
	v_mfma_f32_16x16x32_bf16 v[96:99], v[164:167], v[172:175], v[96:99]
	s_waitcnt lgkmcnt(0)
	v_mfma_f32_16x16x32_bf16 v[120:123], v[64:67], v[168:171], v[120:123]
	v_mfma_f32_16x16x32_bf16 v[112:115], v[72:75], v[168:171], v[112:115]
	v_mfma_f32_16x16x32_bf16 v[88:91], v[64:67], v[172:175], v[88:91]
	v_mfma_f32_16x16x32_bf16 v[80:83], v[72:75], v[172:175], v[80:83]
	v_mfma_f32_16x16x32_bf16 v[48:51], v[72:75], v[194:197], v[48:51]
	v_mfma_f32_16x16x32_bf16 v[202:205], v[160:163], v[168:171], v[132:135]
	v_mfma_f32_16x16x32_bf16 v[206:209], v[160:163], v[172:175], v[104:107]
	v_mfma_f32_16x16x32_bf16 v[44:47], v[160:163], v[198:201], v[44:47]
	v_mfma_f32_16x16x32_bf16 v[40:43], v[164:167], v[198:201], v[40:43]
	v_mfma_f32_16x16x32_bf16 v[220:223], v[64:67], v[194:197], v[56:59]
	v_mfma_f32_16x16x32_bf16 v[36:39], v[64:67], v[198:201], v[36:39]
	v_mfma_f32_16x16x32_bf16 v[32:35], v[72:75], v[198:201], v[32:35]
	s_setprio 0
	s_barrier
; #define G_LOAD(kt_) do { \
;     if constexpr (AF32) { _Pragma("unroll") for (int i = 0; i < 4; ++i) ld16_sc1(ra[i], Af + (size_t)i * 32 * lda + (kt_) * 32); } \
;     else { _Pragma("unroll") for (int i = 0; i < 2; ++i) ld16_sc1(rab[i], Ab + (size_t)i * 64 * lda + (kt_) * 32); } \
;     _Pragma("unroll") for (int i = 0; i < 4; ++i) ld16_sc1(rb[i], Bp + (size_t)(kt_) * bstep + i * 2048); } while (0)
; template <bool AF32, class Epi>
; __device__ __forceinline__ void gemm_tile(unsigned char* smem, const void* Ap, int lda, const bf16_t* WT, int N, int K, const Epi& epi, int m0, int n0,
;                                           GPre& pr, bool preloaded, const void* nAp, int nn0, bool has_next) {
;     ...
;     for (int nh = 0; nh < 4; ++nh) {
;       bf16x8 bfr[2];
; #pragma unroll
;       for (int n2 = 0; n2 < 2; ++n2) bfr[n2] = *(const bf16x8*)(b_s + (nh * 2 + n2) * 16 * GLD);
; #pragma unroll
;       for (int m = 0; m < 4; ++m)
; #pragma unroll
;         for (int n2 = 0; n2 < 2; ++n2) acc[m][nh * 2 + n2] = __builtin_amdgcn_mfma_f32_16x16x32_bf16(bfr[n2], af[m], acc[m][nh * 2 + n2], 0, 0, 0);
;     }
;     __builtin_amdgcn_s_setprio(0);
;     __syncthreads();
;   }
;   if (has_next) {
;     const float* Af = (const float*)nAp + (size_t)(tid >> 3) * lda + (tid & 7) * 4;
;     const bf16_t* Ab = (const bf16_t*)nAp + (size_t)(tid >> 2) * lda + (tid & 3) * 8;
;     const bf16_t* Bp = WT + (size_t)nn0 * 32 + tid * 8;
;     G_LOAD(0);
;   }
	s_setprio 1
	ds_read_b128 v[56:59], v193 offset:40960
	ds_read_b128 v[64:67], v193 offset:42240
	ds_read_b128 v[194:197], v176 offset:30720
	ds_read_b128 v[198:201], v176 offset:32000
	ds_read_b128 v[224:227], v176 offset:33280
	ds_read_b128 v[228:231], v176 offset:34560
	s_waitcnt lgkmcnt(3)
	v_mfma_f32_16x16x32_bf16 v[172:175], v[56:59], v[194:197], v[156:159]
	v_mfma_f32_16x16x32_bf16 v[164:167], v[64:67], v[194:197], v[152:155]
	s_waitcnt lgkmcnt(2)
	v_mfma_f32_16x16x32_bf16 v[140:143], v[56:59], v[198:201], v[140:143]
	v_mfma_f32_16x16x32_bf16 v[132:135], v[64:67], v[198:201], v[136:139]
	s_waitcnt lgkmcnt(1)
	v_mfma_f32_16x16x32_bf16 v[108:111], v[56:59], v[224:227], v[108:111]
	v_mfma_f32_16x16x32_bf16 v[100:103], v[64:67], v[224:227], v[100:103]
	s_waitcnt lgkmcnt(0)
	v_mfma_f32_16x16x32_bf16 v[76:79], v[56:59], v[228:231], v[76:79]
	ds_read_b128 v[56:59], v193 offset:43520
	v_mfma_f32_16x16x32_bf16 v[72:75], v[64:67], v[228:231], v[68:71]
	ds_read_b128 v[64:67], v193 offset:44800
	s_waitcnt lgkmcnt(1)
	v_mfma_f32_16x16x32_bf16 v[168:171], v[56:59], v[194:197], v[148:151]
	s_waitcnt lgkmcnt(0)
	v_mfma_f32_16x16x32_bf16 v[156:159], v[64:67], v[194:197], v[144:147]
	v_mfma_f32_16x16x32_bf16 v[136:139], v[56:59], v[198:201], v[124:127]
	v_mfma_f32_16x16x32_bf16 v[124:127], v[64:67], v[198:201], v[116:119]
	v_mfma_f32_16x16x32_bf16 v[104:107], v[56:59], v[224:227], v[92:95]
	v_mfma_f32_16x16x32_bf16 v[92:95], v[64:67], v[224:227], v[84:87]
	v_mfma_f32_16x16x32_bf16 v[68:71], v[56:59], v[228:231], v[60:63]
	ds_read_b128 v[56:59], v193 offset:46080
	v_mfma_f32_16x16x32_bf16 v[64:67], v[64:67], v[228:231], v[52:55]
	s_nop 2
	ds_read_b128 v[52:55], v193 offset:47360
	s_waitcnt lgkmcnt(1)
	v_mfma_f32_16x16x32_bf16 v[160:163], v[56:59], v[194:197], v[202:205]
	s_waitcnt lgkmcnt(0)
	v_mfma_f32_16x16x32_bf16 v[148:151], v[52:55], v[194:197], v[128:131]
	v_mfma_f32_16x16x32_bf16 v[128:131], v[56:59], v[198:201], v[206:209]
	v_mfma_f32_16x16x32_bf16 v[116:119], v[52:55], v[198:201], v[96:99]
	v_mfma_f32_16x16x32_bf16 v[96:99], v[56:59], v[224:227], v[212:215]
	v_mfma_f32_16x16x32_bf16 v[60:63], v[56:59], v[228:231], v[44:47]
	s_nop 2
	ds_read_b128 v[44:47], v193 offset:48640
	v_mfma_f32_16x16x32_bf16 v[56:59], v[52:55], v[228:231], v[40:43]
	s_nop 2
	ds_read_b128 v[40:43], v193 offset:49920
	v_mfma_f32_16x16x32_bf16 v[84:87], v[52:55], v[224:227], v[216:219]
	s_waitcnt lgkmcnt(1)
	v_mfma_f32_16x16x32_bf16 v[152:155], v[44:47], v[194:197], v[120:123]
	s_waitcnt lgkmcnt(0)
	v_mfma_f32_16x16x32_bf16 v[144:147], v[40:43], v[194:197], v[112:115]
	v_mfma_f32_16x16x32_bf16 v[120:123], v[44:47], v[198:201], v[88:91]
	v_mfma_f32_16x16x32_bf16 v[112:115], v[40:43], v[198:201], v[80:83]
	v_mfma_f32_16x16x32_bf16 v[88:91], v[44:47], v[224:227], v[220:223]
	v_mfma_f32_16x16x32_bf16 v[80:83], v[40:43], v[224:227], v[48:51]
	v_mfma_f32_16x16x32_bf16 v[52:55], v[44:47], v[228:231], v[36:39]
	v_mfma_f32_16x16x32_bf16 v[48:51], v[40:43], v[228:231], v[32:35]
	s_and_b64 vcc, exec, s[6:7]
	s_barrier
	s_cbranch_vccz .LBB0_299
	s_ashr_i32 s51, s50, 31
	s_lshl_b64 s[6:7], s[50:51], 19
	s_add_u32 s6, s10, s6
	s_addc_u32 s7, s11, s7
	s_lshl_b32 s50, s65, 8
	v_lshl_add_u64 v[0:1], v[188:189], 2, s[6:7]
	v_lshlrev_b32_e32 v176, 2, v190
	s_ashr_i32 s51, s50, 31
	v_lshl_add_u64 v[0:1], v[0:1], 0, v[176:177]
	s_lshl_b64 s[6:7], s[50:51], 6
	global_load_dwordx4 v[40:43], v[0:1], off sc1
	s_add_u32 s6, s2, s6
	v_lshl_add_u64 v[2:3], v[0:1], 0, s[14:15]
	global_load_dwordx4 v[44:47], v[2:3], off sc1
	s_addc_u32 s7, s33, s7
	v_lshl_add_u64 v[2:3], v[0:1], 0, s[16:17]
	global_load_dwordx4 v[32:35], v[2:3], off sc1
	v_lshl_add_u64 v[0:1], v[0:1], 0, s[18:19]
	global_load_dwordx4 v[36:39], v[0:1], off sc1
	v_lshl_add_u64 v[12:13], v[184:185], 1, s[6:7]
	global_load_dwordx4 v[0:3], v[12:13], off sc1
	v_lshl_add_u64 v[4:5], v[12:13], 0, s[20:21]
	global_load_dwordx4 v[4:7], v[4:5], off sc1
	v_lshl_add_u64 v[8:9], v[12:13], 0, s[22:23]
	global_load_dwordx4 v[8:11], v[8:9], off sc1
	v_lshl_add_u64 v[12:13], v[12:13], 0, s[24:25]
	global_load_dwordx4 v[12:15], v[12:13], off sc1
	s_branch .LBB0_300

; #define G_LOAD(kt_) do { \
;     if constexpr (AF32) { _Pragma("unroll") for (int i = 0; i < 4; ++i) ld16_sc1(ra[i], Af + (size_t)i * 32 * lda + (kt_) * 32); } \
;     else { _Pragma("unroll") for (int i = 0; i < 2; ++i) ld16_sc1(rab[i], Ab + (size_t)i * 64 * lda + (kt_) * 32); } \
;     _Pragma("unroll") for (int i = 0; i < 4; ++i) ld16_sc1(rb[i], Bp + (size_t)(kt_) * bstep + i * 2048); } while (0)
; template <bool AF32, class Epi>
; __device__ __forceinline__ void gemm_tile(unsigned char* smem, const void* Ap, int lda, const bf16_t* WT, int N, int K, const Epi& epi, int m0, int n0,
;                                           GPre& pr, bool preloaded, const void* nAp, int nn0, bool has_next) {
;     ...
;   if (!preloaded) G_LOAD(0);
;   G_STORE(0);
;   if (nk > 1) G_LOAD(1);
;   __syncthreads();
;   for (int kt = 0; kt < nk; ++kt) {
;     const int cur = kt & 1;
;     if (kt + 1 < nk) G_STORE(cur ^ 1);
;     if (kt + 2 < nk) G_LOAD(kt + 2);
;     const bf16_t* a_s = sbase + cur * G_STAGE + (wr * 64 + l15) * GLD + quad * 8;
;     const bf16_t* b_s = sbase + cur * G_STAGE + 128 * GLD + (wc * 128 + l15) * GLD + quad * 8;
;     __builtin_amdgcn_s_setprio(1);
;     bf16x8 af[4];
; #pragma unroll
;     for (int m = 0; m < 4; ++m) af[m] = *(const bf16x8*)(a_s + m * 16 * GLD);
; #pragma unroll
;     for (int nh = 0; nh < 4; ++nh) {
;       bf16x8 bfr[2];
; #pragma unroll
;       for (int n2 = 0; n2 < 2; ++n2) bfr[n2] = *(const bf16x8*)(b_s + (nh * 2 + n2) * 16 * GLD);
; #pragma unroll
;       for (int m = 0; m < 4; ++m)
; #pragma unroll
;         for (int n2 = 0; n2 < 2; ++n2) acc[m][nh * 2 + n2] = __builtin_amdgcn_mfma_f32_16x16x32_bf16(bfr[n2], af[m], acc[m][nh * 2 + n2], 0, 0, 0);
;     }
;     __builtin_amdgcn_s_setprio(0);
;     __syncthreads();
;   }
.LBB0_389:
	s_and_b32 s3, s51, 1
	s_waitcnt vmcnt(0)
	s_xor_b32 s52, s3, 1
	s_mulk_i32 s52, 0x7800
	v_lshl_add_u32 v176, v162, 1, s52
	ds_write_b128 v176, v[0:3] offset:10240
	ds_write_b128 v176, v[4:7] offset:15360
	ds_write_b128 v176, v[8:11] offset:20480
	ds_write_b128 v176, v[12:15] offset:25600
	s_setprio 2
	global_load_dwordx4 v[0:3], v[164:165], off sc1
	v_lshl_add_u64 v[196:197], v[164:165], 0, s[22:23]
	global_load_dwordx4 v[4:7], v[196:197], off sc1
	v_lshl_add_u64 v[198:199], v[164:165], 0, s[24:25]
	global_load_dwordx4 v[8:11], v[198:199], off sc1
	v_lshl_add_u64 v[200:201], v[164:165], 0, s[26:27]
	global_load_dwordx4 v[12:15], v[200:201], off sc1
	s_setprio 0
	v_cvt_pk_bf16_f32 v202, v44, v45
	v_mov_b32_e32 v205, v44
	v_mov_b32_e32 v44, v41
	v_lshl_add_u32 v171, v160, 1, s52
	v_cvt_pk_bf16_f32 v203, v46, v47
	v_mov_b32_e32 v204, v40
	v_mov_b32_e32 v206, v42
	v_mov_b32_e32 v207, v46
	v_mov_b32_e32 v46, v43
	v_cvt_pk_bf16_f32 v40, v40, v41
	v_cvt_pk_bf16_f32 v41, v42, v43
	v_cvt_pk_bf16_f32 v42, v36, v37
	v_cvt_pk_bf16_f32 v43, v38, v39
	v_mov_b32_e32 v208, v32
	v_mov_b32_e32 v209, v36
	v_mov_b32_e32 v36, v33
	v_mov_b32_e32 v212, v34
	v_mov_b32_e32 v213, v38
	v_mov_b32_e32 v38, v35
	v_cvt_pk_bf16_f32 v32, v32, v33
	v_cvt_pk_bf16_f32 v33, v34, v35
	v_pk_mul_f32 v[34:35], v[44:45], v[44:45]
	ds_write2st64_b64 v171, v[202:203], v[40:41] offset1:5
	ds_write2st64_b64 v171, v[42:43], v[32:33] offset0:10 offset1:15
	v_pk_fma_f32 v[216:217], v[204:205], v[204:205], v[34:35]
	v_pk_mul_f32 v[36:37], v[36:37], v[36:37]
	v_pk_fma_f32 v[216:217], v[206:207], v[206:207], v[216:217]
	v_pk_fma_f32 v[218:219], v[208:209], v[208:209], v[36:37]
	v_pk_fma_f32 v[202:203], v[46:47], v[46:47], v[216:217]
	s_setprio 2
	global_load_dwordx4 v[44:47], v[166:167], off sc1
	v_lshl_add_u64 v[172:173], v[166:167], 0, s[16:17]
	v_pk_fma_f32 v[218:219], v[212:213], v[212:213], v[218:219]
	global_load_dwordx4 v[40:43], v[172:173], off sc1
	v_lshl_add_u64 v[174:175], v[166:167], 0, s[18:19]
	v_pk_fma_f32 v[204:205], v[38:39], v[38:39], v[218:219]
	global_load_dwordx4 v[36:39], v[174:175], off sc1
	v_lshl_add_u64 v[194:195], v[166:167], 0, s[20:21]
	global_load_dwordx4 v[32:35], v[194:195], off sc1
	s_setprio 0
	s_add_i32 s51, s51, 1
	s_mulk_i32 s3, 0x7800
	v_pk_add_f32 v[184:185], v[184:185], v[202:203]
	v_pk_add_f32 v[180:181], v[180:181], v[204:205]
	v_add3_u32 v171, s3, v169, v170
	s_setprio 1
	v_add3_u32 v176, s3, v168, v170
	ds_read_b128 v[172:175], v176 offset:10240
	ds_read_b128 v[194:197], v176 offset:11520
	ds_read_b128 v[198:201], v171
	ds_read_b128 v[202:205], v171 offset:1280
	ds_read_b128 v[206:209], v171 offset:2560
	ds_read_b128 v[212:215], v171 offset:3840
	s_waitcnt lgkmcnt(3)
	v_mfma_f32_16x16x32_bf16 v[156:159], v[172:175], v[198:201], v[156:159]
	v_mfma_f32_16x16x32_bf16 v[152:155], v[194:197], v[198:201], v[152:155]
	s_waitcnt lgkmcnt(2)
	v_mfma_f32_16x16x32_bf16 v[140:143], v[172:175], v[202:205], v[140:143]
	v_mfma_f32_16x16x32_bf16 v[136:139], v[194:197], v[202:205], v[136:139]
	s_waitcnt lgkmcnt(1)
	v_mfma_f32_16x16x32_bf16 v[108:111], v[172:175], v[206:209], v[108:111]
	v_mfma_f32_16x16x32_bf16 v[100:103], v[194:197], v[206:209], v[100:103]
	s_waitcnt lgkmcnt(0)
	v_mfma_f32_16x16x32_bf16 v[76:79], v[172:175], v[212:215], v[76:79]
	ds_read_b128 v[172:175], v176 offset:12800
	v_mfma_f32_16x16x32_bf16 v[68:71], v[194:197], v[212:215], v[68:71]
	ds_read_b128 v[194:197], v176 offset:14080
	s_waitcnt lgkmcnt(1)
	v_mfma_f32_16x16x32_bf16 v[148:151], v[172:175], v[198:201], v[148:151]
	s_waitcnt lgkmcnt(0)
	v_mfma_f32_16x16x32_bf16 v[144:147], v[194:197], v[198:201], v[144:147]
	v_mfma_f32_16x16x32_bf16 v[124:127], v[172:175], v[202:205], v[124:127]
	v_mfma_f32_16x16x32_bf16 v[116:119], v[194:197], v[202:205], v[116:119]
	v_mfma_f32_16x16x32_bf16 v[92:95], v[172:175], v[206:209], v[92:95]
	v_mfma_f32_16x16x32_bf16 v[84:87], v[194:197], v[206:209], v[84:87]
	v_mfma_f32_16x16x32_bf16 v[60:63], v[172:175], v[212:215], v[60:63]
	ds_read_b128 v[172:175], v176 offset:15360
	v_mfma_f32_16x16x32_bf16 v[52:55], v[194:197], v[212:215], v[52:55]
	ds_read_b128 v[194:197], v176 offset:16640
	s_waitcnt lgkmcnt(1)
	v_mfma_f32_16x16x32_bf16 v[132:135], v[172:175], v[198:201], v[132:135]
	s_waitcnt lgkmcnt(0)
	v_mfma_f32_16x16x32_bf16 v[128:131], v[194:197], v[198:201], v[128:131]
	v_mfma_f32_16x16x32_bf16 v[104:107], v[172:175], v[202:205], v[104:107]
	v_mfma_f32_16x16x32_bf16 v[96:99], v[194:197], v[202:205], v[96:99]
	v_mfma_f32_16x16x32_bf16 v[72:75], v[172:175], v[206:209], v[72:75]
	v_mfma_f32_16x16x32_bf16 v[64:67], v[194:197], v[206:209], v[64:67]
	v_mfma_f32_16x16x32_bf16 v[28:31], v[172:175], v[212:215], v[28:31]
	ds_read_b128 v[172:175], v176 offset:17920
	v_mfma_f32_16x16x32_bf16 v[24:27], v[194:197], v[212:215], v[24:27]
	ds_read_b128 v[194:197], v176 offset:19200
	s_waitcnt lgkmcnt(1)
	v_mfma_f32_16x16x32_bf16 v[120:123], v[172:175], v[198:201], v[120:123]
	s_waitcnt lgkmcnt(0)
	v_mfma_f32_16x16x32_bf16 v[112:115], v[194:197], v[198:201], v[112:115]
	v_mfma_f32_16x16x32_bf16 v[88:91], v[172:175], v[202:205], v[88:91]
	v_mfma_f32_16x16x32_bf16 v[80:83], v[194:197], v[202:205], v[80:83]
	v_mfma_f32_16x16x32_bf16 v[56:59], v[172:175], v[206:209], v[56:59]
	v_mfma_f32_16x16x32_bf16 v[48:51], v[194:197], v[206:209], v[48:51]
	v_mfma_f32_16x16x32_bf16 v[20:23], v[172:175], v[212:215], v[20:23]
	v_mfma_f32_16x16x32_bf16 v[16:19], v[194:197], v[212:215], v[16:19]
	s_setprio 0
	v_lshl_add_u64 v[164:165], v[164:165], 0, s[38:39]
	s_cmp_eq_u32 s51, 30
	v_lshl_add_u64 v[166:167], v[166:167], 0, s[28:29]
	s_barrier
	s_cbranch_scc0 .LBB0_389
; #define G_LOAD(kt_) do { \
;     if constexpr (AF32) { _Pragma("unroll") for (int i = 0; i < 4; ++i) ld16_sc1(ra[i], Af + (size_t)i * 32 * lda + (kt_) * 32); } \
;     else { _Pragma("unroll") for (int i = 0; i < 2; ++i) ld16_sc1(rab[i], Ab + (size_t)i * 64 * lda + (kt_) * 32); } \
;     _Pragma("unroll") for (int i = 0; i < 4; ++i) ld16_sc1(rb[i], Bp + (size_t)(kt_) * bstep + i * 2048); } while (0)
; template <bool AF32, class Epi>
; __device__ __forceinline__ void gemm_tile(unsigned char* smem, const void* Ap, int lda, const bf16_t* WT, int N, int K, const Epi& epi, int m0, int n0,
;                                           GPre& pr, bool preloaded, const void* nAp, int nn0, bool has_next) {
;     ...
;   if (!preloaded) G_LOAD(0);
;   G_STORE(0);
;   if (nk > 1) G_LOAD(1);
;   __syncthreads();
;   for (int kt = 0; kt < nk; ++kt) {
;     const int cur = kt & 1;
;     if (kt + 1 < nk) G_STORE(cur ^ 1);
;     if (kt + 2 < nk) G_LOAD(kt + 2);
;     const bf16_t* a_s = sbase + cur * G_STAGE + (wr * 64 + l15) * GLD + quad * 8;
;     const bf16_t* b_s = sbase + cur * G_STAGE + 128 * GLD + (wc * 128 + l15) * GLD + quad * 8;
;     __builtin_amdgcn_s_setprio(1);
;     bf16x8 af[4];
; #pragma unroll
;     for (int m = 0; m < 4; ++m) af[m] = *(const bf16x8*)(a_s + m * 16 * GLD);
; #pragma unroll
;     for (int nh = 0; nh < 4; ++nh) {
;       bf16x8 bfr[2];
; #pragma unroll
;       for (int n2 = 0; n2 < 2; ++n2) bfr[n2] = *(const bf16x8*)(b_s + (nh * 2 + n2) * 16 * GLD);
; #pragma unroll
;       for (int m = 0; m < 4; ++m)
; #pragma unroll
;         for (int n2 = 0; n2 < 2; ++n2) acc[m][nh * 2 + n2] = __builtin_amdgcn_mfma_f32_16x16x32_bf16(bfr[n2], af[m], acc[m][nh * 2 + n2], 0, 0, 0);
;     }
;     __builtin_amdgcn_s_setprio(0);
;     __syncthreads();
	s_waitcnt vmcnt(0)
	v_add_u32_e32 v176, v169, v170
	v_cvt_pk_bf16_f32 v164, v44, v45
	v_cvt_pk_bf16_f32 v165, v46, v47
	v_cvt_pk_bf16_f32 v166, v40, v41
	v_cvt_pk_bf16_f32 v167, v42, v43
	ds_write2st64_b64 v161, v[164:165], v[166:167] offset0:60 offset1:65
	v_cvt_pk_bf16_f32 v164, v36, v37
	v_cvt_pk_bf16_f32 v165, v38, v39
	v_cvt_pk_bf16_f32 v166, v32, v33
	v_cvt_pk_bf16_f32 v167, v34, v35
	ds_write2st64_b64 v161, v[164:165], v[166:167] offset0:70 offset1:75
	ds_write_b128 v163, v[0:3] offset:40960
	ds_write_b128 v163, v[4:7] offset:46080
	ds_write_b128 v163, v[8:11] offset:51200
	ds_write_b128 v163, v[12:15] offset:56320
	s_setprio 1
	v_add_u32_e32 v193, v168, v170
	ds_read_b128 v[160:163], v193 offset:10240
	ds_read_b128 v[164:167], v193 offset:11520
	ds_read_b128 v[168:171], v176
	ds_read_b128 v[172:175], v176 offset:1280
	ds_read_b128 v[194:197], v176 offset:2560
	ds_read_b128 v[198:201], v176 offset:3840
	s_waitcnt lgkmcnt(3)
	v_mfma_f32_16x16x32_bf16 v[156:159], v[160:163], v[168:171], v[156:159]
	v_mfma_f32_16x16x32_bf16 v[152:155], v[164:167], v[168:171], v[152:155]
	s_waitcnt lgkmcnt(2)
	v_mfma_f32_16x16x32_bf16 v[140:143], v[160:163], v[172:175], v[140:143]
	v_mfma_f32_16x16x32_bf16 v[136:139], v[164:167], v[172:175], v[136:139]
	s_waitcnt lgkmcnt(1)
	v_mfma_f32_16x16x32_bf16 v[108:111], v[160:163], v[194:197], v[108:111]
	v_mfma_f32_16x16x32_bf16 v[100:103], v[164:167], v[194:197], v[100:103]
	s_waitcnt lgkmcnt(0)
	v_mfma_f32_16x16x32_bf16 v[76:79], v[160:163], v[198:201], v[76:79]
	ds_read_b128 v[160:163], v193 offset:12800
	v_mfma_f32_16x16x32_bf16 v[68:71], v[164:167], v[198:201], v[68:71]
	ds_read_b128 v[164:167], v193 offset:14080
	s_waitcnt lgkmcnt(1)
	v_mfma_f32_16x16x32_bf16 v[148:151], v[160:163], v[168:171], v[148:151]
	s_waitcnt lgkmcnt(0)
	v_mfma_f32_16x16x32_bf16 v[144:147], v[164:167], v[168:171], v[144:147]
	v_mfma_f32_16x16x32_bf16 v[124:127], v[160:163], v[172:175], v[124:127]
	v_mfma_f32_16x16x32_bf16 v[116:119], v[164:167], v[172:175], v[116:119]
	v_mfma_f32_16x16x32_bf16 v[92:95], v[160:163], v[194:197], v[92:95]
	v_mfma_f32_16x16x32_bf16 v[84:87], v[164:167], v[194:197], v[84:87]
	v_mfma_f32_16x16x32_bf16 v[60:63], v[160:163], v[198:201], v[60:63]
	ds_read_b128 v[160:163], v193 offset:15360
	v_mfma_f32_16x16x32_bf16 v[52:55], v[164:167], v[198:201], v[52:55]
	ds_read_b128 v[164:167], v193 offset:16640
	s_waitcnt lgkmcnt(1)
	v_mfma_f32_16x16x32_bf16 v[220:223], v[160:163], v[194:197], v[72:75]
	s_nop 2
	ds_read_b128 v[72:75], v193 offset:19200
	s_waitcnt lgkmcnt(1)
	v_mfma_f32_16x16x32_bf16 v[224:227], v[164:167], v[194:197], v[64:67]
	s_nop 2
	ds_read_b128 v[64:67], v193 offset:17920
	s_waitcnt lgkmcnt(1)
	v_mfma_f32_16x16x32_bf16 v[112:115], v[72:75], v[168:171], v[112:115]
	v_mfma_f32_16x16x32_bf16 v[80:83], v[72:75], v[172:175], v[80:83]
	v_mfma_f32_16x16x32_bf16 v[48:51], v[72:75], v[194:197], v[48:51]
	v_mfma_f32_16x16x32_bf16 v[202:205], v[160:163], v[168:171], v[132:135]
	v_mfma_f32_16x16x32_bf16 v[206:209], v[164:167], v[168:171], v[128:131]
	v_mfma_f32_16x16x32_bf16 v[212:215], v[160:163], v[172:175], v[104:107]
	v_mfma_f32_16x16x32_bf16 v[216:219], v[164:167], v[172:175], v[96:99]
	v_mfma_f32_16x16x32_bf16 v[28:31], v[160:163], v[198:201], v[28:31]
	v_mfma_f32_16x16x32_bf16 v[24:27], v[164:167], v[198:201], v[24:27]
	s_waitcnt lgkmcnt(0)
	v_mfma_f32_16x16x32_bf16 v[228:231], v[64:67], v[168:171], v[120:123]
	v_mfma_f32_16x16x32_bf16 v[232:235], v[64:67], v[172:175], v[88:91]
	v_mfma_f32_16x16x32_bf16 v[236:239], v[64:67], v[194:197], v[56:59]
	v_mfma_f32_16x16x32_bf16 v[20:23], v[64:67], v[198:201], v[20:23]
	v_mfma_f32_16x16x32_bf16 v[16:19], v[72:75], v[198:201], v[16:19]
	s_setprio 0
	s_barrier
; #define G_LOAD(kt_) do { \
;     if constexpr (AF32) { _Pragma("unroll") for (int i = 0; i < 4; ++i) ld16_sc1(ra[i], Af + (size_t)i * 32 * lda + (kt_) * 32); } \
;     else { _Pragma("unroll") for (int i = 0; i < 2; ++i) ld16_sc1(rab[i], Ab + (size_t)i * 64 * lda + (kt_) * 32); } \
;     _Pragma("unroll") for (int i = 0; i < 4; ++i) ld16_sc1(rb[i], Bp + (size_t)(kt_) * bstep + i * 2048); } while (0)
; template <bool AF32, class Epi>
; __device__ __forceinline__ void gemm_tile(unsigned char* smem, const void* Ap, int lda, const bf16_t* WT, int N, int K, const Epi& epi, int m0, int n0,
;                                           GPre& pr, bool preloaded, const void* nAp, int nn0, bool has_next) {
;     ...
;   for (int kt = 0; kt < nk; ++kt) {
;     const int cur = kt & 1;
;     if (kt + 1 < nk) G_STORE(cur ^ 1);
;     if (kt + 2 < nk) G_LOAD(kt + 2);
;     const bf16_t* a_s = sbase + cur * G_STAGE + (wr * 64 + l15) * GLD + quad * 8;
;     const bf16_t* b_s = sbase + cur * G_STAGE + 128 * GLD + (wc * 128 + l15) * GLD + quad * 8;
;     __builtin_amdgcn_s_setprio(1);
;     bf16x8 af[4];
; #pragma unroll
;     for (int m = 0; m < 4; ++m) af[m] = *(const bf16x8*)(a_s + m * 16 * GLD);
; #pragma unroll
;     for (int nh = 0; nh < 4; ++nh) {
;       bf16x8 bfr[2];
; #pragma unroll
;       for (int n2 = 0; n2 < 2; ++n2) bfr[n2] = *(const bf16x8*)(b_s + (nh * 2 + n2) * 16 * GLD);
; #pragma unroll
;       for (int m = 0; m < 4; ++m)
; #pragma unroll
;         for (int n2 = 0; n2 < 2; ++n2) acc[m][nh * 2 + n2] = __builtin_amdgcn_mfma_f32_16x16x32_bf16(bfr[n2], af[m], acc[m][nh * 2 + n2], 0, 0, 0);
;     }
;     __builtin_amdgcn_s_setprio(0);
;     __syncthreads();
;   }
;   if (has_next) {
;     const float* Af = (const float*)nAp + (size_t)(tid >> 3) * lda + (tid & 7) * 4;
;     const bf16_t* Ab = (const bf16_t*)nAp + (size_t)(tid >> 2) * lda + (tid & 3) * 8;
;     const bf16_t* Bp = WT + (size_t)nn0 * 32 + tid * 8;
;     G_LOAD(0);
;   }
	s_setprio 1
	ds_read_b128 v[56:59], v193 offset:40960
	ds_read_b128 v[64:67], v193 offset:42240
	ds_read_b128 v[194:197], v176 offset:30720
	ds_read_b128 v[198:201], v176 offset:32000
	ds_read_b128 v[240:243], v176 offset:33280
	ds_read_b128 v[244:247], v176 offset:34560
	s_waitcnt lgkmcnt(3)
	v_mfma_f32_16x16x32_bf16 v[172:175], v[56:59], v[194:197], v[156:159]
	v_mfma_f32_16x16x32_bf16 v[168:171], v[64:67], v[194:197], v[152:155]
	s_waitcnt lgkmcnt(2)
	v_mfma_f32_16x16x32_bf16 v[140:143], v[56:59], v[198:201], v[140:143]
	v_mfma_f32_16x16x32_bf16 v[136:139], v[64:67], v[198:201], v[136:139]
	s_waitcnt lgkmcnt(1)
	v_mfma_f32_16x16x32_bf16 v[108:111], v[56:59], v[240:243], v[108:111]
	v_mfma_f32_16x16x32_bf16 v[104:107], v[64:67], v[240:243], v[100:103]
	s_waitcnt lgkmcnt(0)
	v_mfma_f32_16x16x32_bf16 v[76:79], v[56:59], v[244:247], v[76:79]
	ds_read_b128 v[56:59], v193 offset:43520
	v_mfma_f32_16x16x32_bf16 v[72:75], v[64:67], v[244:247], v[68:71]
	ds_read_b128 v[64:67], v193 offset:44800
	s_waitcnt lgkmcnt(1)
	v_mfma_f32_16x16x32_bf16 v[164:167], v[56:59], v[194:197], v[148:151]
	s_waitcnt lgkmcnt(0)
	v_mfma_f32_16x16x32_bf16 v[160:163], v[64:67], v[194:197], v[144:147]
	v_mfma_f32_16x16x32_bf16 v[132:135], v[56:59], v[198:201], v[124:127]
	v_mfma_f32_16x16x32_bf16 v[128:131], v[64:67], v[198:201], v[116:119]
	v_mfma_f32_16x16x32_bf16 v[100:103], v[56:59], v[240:243], v[92:95]
	v_mfma_f32_16x16x32_bf16 v[96:99], v[64:67], v[240:243], v[84:87]
	v_mfma_f32_16x16x32_bf16 v[68:71], v[56:59], v[244:247], v[60:63]
	ds_read_b128 v[56:59], v193 offset:46080
	v_mfma_f32_16x16x32_bf16 v[64:67], v[64:67], v[244:247], v[52:55]
	s_nop 2
	ds_read_b128 v[52:55], v193 offset:47360
	s_waitcnt lgkmcnt(1)
	v_mfma_f32_16x16x32_bf16 v[156:159], v[56:59], v[194:197], v[202:205]
	v_mfma_f32_16x16x32_bf16 v[124:127], v[56:59], v[198:201], v[212:215]
	v_mfma_f32_16x16x32_bf16 v[92:95], v[56:59], v[240:243], v[220:223]
	v_mfma_f32_16x16x32_bf16 v[60:63], v[56:59], v[244:247], v[28:31]
	s_nop 2
	ds_read_b128 v[28:31], v193 offset:48640
	s_waitcnt lgkmcnt(1)
	v_mfma_f32_16x16x32_bf16 v[56:59], v[52:55], v[244:247], v[24:27]
	s_nop 2
	ds_read_b128 v[24:27], v193 offset:49920
	v_mfma_f32_16x16x32_bf16 v[152:155], v[52:55], v[194:197], v[206:209]
	v_mfma_f32_16x16x32_bf16 v[120:123], v[52:55], v[198:201], v[216:219]
	v_mfma_f32_16x16x32_bf16 v[88:91], v[52:55], v[240:243], v[224:227]
	s_waitcnt lgkmcnt(1)
	v_mfma_f32_16x16x32_bf16 v[148:151], v[28:31], v[194:197], v[228:231]
	s_waitcnt lgkmcnt(0)
	v_mfma_f32_16x16x32_bf16 v[144:147], v[24:27], v[194:197], v[112:115]
	v_mfma_f32_16x16x32_bf16 v[116:119], v[28:31], v[198:201], v[232:235]
	v_mfma_f32_16x16x32_bf16 v[112:115], v[24:27], v[198:201], v[80:83]
	v_mfma_f32_16x16x32_bf16 v[84:87], v[28:31], v[240:243], v[236:239]
	v_mfma_f32_16x16x32_bf16 v[80:83], v[24:27], v[240:243], v[48:51]
	v_mfma_f32_16x16x32_bf16 v[52:55], v[28:31], v[244:247], v[20:23]
	v_mfma_f32_16x16x32_bf16 v[48:51], v[24:27], v[244:247], v[16:19]
	s_and_b64 vcc, exec, s[6:7]
	s_barrier
	s_cbranch_vccz .LBB0_392
	s_ashr_i32 s51, s50, 31
	s_lshl_b64 s[6:7], s[50:51], 19
	s_add_u32 s6, s12, s6
	s_addc_u32 s7, s13, s7
	s_lshl_b32 s50, s67, 8
	v_lshl_add_u64 v[0:1], v[186:187], 2, s[6:7]
	v_lshlrev_b32_e32 v176, 2, v188
	s_ashr_i32 s51, s50, 31
	v_lshl_add_u64 v[0:1], v[0:1], 0, v[176:177]
	s_lshl_b64 s[6:7], s[50:51], 6
	global_load_dwordx4 v[24:27], v[0:1], off sc1
	s_add_u32 s6, s2, s6
	v_lshl_add_u64 v[2:3], v[0:1], 0, s[16:17]
	global_load_dwordx4 v[28:31], v[2:3], off sc1
	s_addc_u32 s7, s33, s7
	v_lshl_add_u64 v[2:3], v[0:1], 0, s[18:19]
	global_load_dwordx4 v[16:19], v[2:3], off sc1
	v_lshl_add_u64 v[0:1], v[0:1], 0, s[20:21]
	global_load_dwordx4 v[20:23], v[0:1], off sc1
	v_lshl_add_u64 v[12:13], v[182:183], 1, s[6:7]
	global_load_dwordx4 v[0:3], v[12:13], off sc1
	v_lshl_add_u64 v[4:5], v[12:13], 0, s[22:23]
	global_load_dwordx4 v[4:7], v[4:5], off sc1
	v_lshl_add_u64 v[8:9], v[12:13], 0, s[24:25]
	global_load_dwordx4 v[8:11], v[8:9], off sc1
	v_lshl_add_u64 v[12:13], v[12:13], 0, s[26:27]
	global_load_dwordx4 v[12:15], v[12:13], off sc1
	s_branch .LBB0_393

; #define G_LOAD(kt_) do { \
;     if constexpr (AF32) { _Pragma("unroll") for (int i = 0; i < 4; ++i) ld16_sc1(ra[i], Af + (size_t)i * 32 * lda + (kt_) * 32); } \
;     else { _Pragma("unroll") for (int i = 0; i < 2; ++i) ld16_sc1(rab[i], Ab + (size_t)i * 64 * lda + (kt_) * 32); } \
;     _Pragma("unroll") for (int i = 0; i < 4; ++i) ld16_sc1(rb[i], Bp + (size_t)(kt_) * bstep + i * 2048); } while (0)
; template <bool AF32, class Epi>
; __device__ __forceinline__ void gemm_tile(unsigned char* smem, const void* Ap, int lda, const bf16_t* WT, int N, int K, const Epi& epi, int m0, int n0,
;                                           GPre& pr, bool preloaded, const void* nAp, int nn0, bool has_next) {
;     ...
;   if (!preloaded) G_LOAD(0);
;   G_STORE(0);
;   if (nk > 1) G_LOAD(1);
;   __syncthreads();
;   for (int kt = 0; kt < nk; ++kt) {
;     const int cur = kt & 1;
;     if (kt + 1 < nk) G_STORE(cur ^ 1);
;     if (kt + 2 < nk) G_LOAD(kt + 2);
;     const bf16_t* a_s = sbase + cur * G_STAGE + (wr * 64 + l15) * GLD + quad * 8;
;     const bf16_t* b_s = sbase + cur * G_STAGE + 128 * GLD + (wc * 128 + l15) * GLD + quad * 8;
;     __builtin_amdgcn_s_setprio(1);
;     bf16x8 af[4];
; #pragma unroll
;     for (int m = 0; m < 4; ++m) af[m] = *(const bf16x8*)(a_s + m * 16 * GLD);
; #pragma unroll
;     for (int nh = 0; nh < 4; ++nh) {
;       bf16x8 bfr[2];
; #pragma unroll
;       for (int n2 = 0; n2 < 2; ++n2) bfr[n2] = *(const bf16x8*)(b_s + (nh * 2 + n2) * 16 * GLD);
; #pragma unroll
;       for (int m = 0; m < 4; ++m)
; #pragma unroll
;         for (int n2 = 0; n2 < 2; ++n2) acc[m][nh * 2 + n2] = __builtin_amdgcn_mfma_f32_16x16x32_bf16(bfr[n2], af[m], acc[m][nh * 2 + n2], 0, 0, 0);
;     }
;     __builtin_amdgcn_s_setprio(0);
;     __syncthreads();
;   }
.LBB0_460:
	s_and_b32 s3, s51, 1
	s_waitcnt vmcnt(0)
	s_xor_b32 s53, s3, 1
	s_mulk_i32 s53, 0x7800
	v_lshl_add_u32 v176, v162, 1, s53
	ds_write_b128 v176, v[0:3] offset:10240
	ds_write_b128 v176, v[4:7] offset:15360
	ds_write_b128 v176, v[8:11] offset:20480
	ds_write_b128 v176, v[12:15] offset:25600
	s_setprio 2
	global_load_dwordx4 v[0:3], v[164:165], off sc1
	v_lshl_add_u64 v[196:197], v[164:165], 0, s[22:23]
	global_load_dwordx4 v[4:7], v[196:197], off sc1
	v_lshl_add_u64 v[198:199], v[164:165], 0, s[24:25]
	global_load_dwordx4 v[8:11], v[198:199], off sc1
	v_lshl_add_u64 v[200:201], v[164:165], 0, s[26:27]
	global_load_dwordx4 v[12:15], v[200:201], off sc1
	s_setprio 0
	v_cvt_pk_bf16_f32 v202, v28, v29
	v_mov_b32_e32 v205, v28
	v_mov_b32_e32 v28, v25
	v_lshl_add_u32 v171, v160, 1, s53
	v_cvt_pk_bf16_f32 v203, v30, v31
	v_mov_b32_e32 v204, v24
	v_mov_b32_e32 v206, v26
	v_mov_b32_e32 v207, v30
	v_mov_b32_e32 v30, v27
	v_cvt_pk_bf16_f32 v24, v24, v25
	v_cvt_pk_bf16_f32 v25, v26, v27
	v_cvt_pk_bf16_f32 v26, v20, v21
	v_cvt_pk_bf16_f32 v27, v22, v23
	v_mov_b32_e32 v208, v16
	v_mov_b32_e32 v209, v20
	v_mov_b32_e32 v20, v17
	v_mov_b32_e32 v212, v18
	v_mov_b32_e32 v213, v22
	v_mov_b32_e32 v22, v19
	v_cvt_pk_bf16_f32 v16, v16, v17
	v_cvt_pk_bf16_f32 v17, v18, v19
	v_pk_mul_f32 v[18:19], v[28:29], v[28:29]
	ds_write2st64_b64 v171, v[202:203], v[24:25] offset1:5
	ds_write2st64_b64 v171, v[26:27], v[16:17] offset0:10 offset1:15
	v_pk_fma_f32 v[216:217], v[204:205], v[204:205], v[18:19]
	v_pk_mul_f32 v[20:21], v[20:21], v[20:21]
	v_pk_fma_f32 v[216:217], v[206:207], v[206:207], v[216:217]
	v_pk_fma_f32 v[218:219], v[208:209], v[208:209], v[20:21]
	v_pk_fma_f32 v[202:203], v[30:31], v[30:31], v[216:217]
	s_setprio 2
	global_load_dwordx4 v[28:31], v[166:167], off sc1
	v_lshl_add_u64 v[172:173], v[166:167], 0, s[16:17]
	v_pk_fma_f32 v[218:219], v[212:213], v[212:213], v[218:219]
	global_load_dwordx4 v[24:27], v[172:173], off sc1
	v_lshl_add_u64 v[174:175], v[166:167], 0, s[18:19]
	v_pk_fma_f32 v[204:205], v[22:23], v[22:23], v[218:219]
	global_load_dwordx4 v[20:23], v[174:175], off sc1
	v_lshl_add_u64 v[194:195], v[166:167], 0, s[20:21]
	global_load_dwordx4 v[16:19], v[194:195], off sc1
	s_setprio 0
	s_add_i32 s51, s51, 1
	s_mulk_i32 s3, 0x7800
	v_pk_add_f32 v[186:187], v[186:187], v[202:203]
	v_pk_add_f32 v[182:183], v[182:183], v[204:205]
	v_add3_u32 v171, s3, v169, v170
	s_setprio 1
	v_add3_u32 v176, s3, v168, v170
	ds_read_b128 v[172:175], v176 offset:10240
	ds_read_b128 v[194:197], v176 offset:11520
	ds_read_b128 v[198:201], v171
	ds_read_b128 v[202:205], v171 offset:1280
	ds_read_b128 v[206:209], v171 offset:2560
	ds_read_b128 v[212:215], v171 offset:3840
	s_waitcnt lgkmcnt(3)
	v_mfma_f32_16x16x32_bf16 v[156:159], v[172:175], v[198:201], v[156:159]
	v_mfma_f32_16x16x32_bf16 v[152:155], v[194:197], v[198:201], v[152:155]
	s_waitcnt lgkmcnt(2)
	v_mfma_f32_16x16x32_bf16 v[140:143], v[172:175], v[202:205], v[140:143]
	v_mfma_f32_16x16x32_bf16 v[136:139], v[194:197], v[202:205], v[136:139]
	s_waitcnt lgkmcnt(1)
	v_mfma_f32_16x16x32_bf16 v[108:111], v[172:175], v[206:209], v[108:111]
	v_mfma_f32_16x16x32_bf16 v[100:103], v[194:197], v[206:209], v[100:103]
	s_waitcnt lgkmcnt(0)
	v_mfma_f32_16x16x32_bf16 v[76:79], v[172:175], v[212:215], v[76:79]
	ds_read_b128 v[172:175], v176 offset:12800
	v_mfma_f32_16x16x32_bf16 v[68:71], v[194:197], v[212:215], v[68:71]
	ds_read_b128 v[194:197], v176 offset:14080
	s_waitcnt lgkmcnt(1)
	v_mfma_f32_16x16x32_bf16 v[148:151], v[172:175], v[198:201], v[148:151]
	s_waitcnt lgkmcnt(0)
	v_mfma_f32_16x16x32_bf16 v[144:147], v[194:197], v[198:201], v[144:147]
	v_mfma_f32_16x16x32_bf16 v[124:127], v[172:175], v[202:205], v[124:127]
	v_mfma_f32_16x16x32_bf16 v[116:119], v[194:197], v[202:205], v[116:119]
	v_mfma_f32_16x16x32_bf16 v[92:95], v[172:175], v[206:209], v[92:95]
	v_mfma_f32_16x16x32_bf16 v[84:87], v[194:197], v[206:209], v[84:87]
	v_mfma_f32_16x16x32_bf16 v[60:63], v[172:175], v[212:215], v[60:63]
	ds_read_b128 v[172:175], v176 offset:15360
	v_mfma_f32_16x16x32_bf16 v[52:55], v[194:197], v[212:215], v[52:55]
	ds_read_b128 v[194:197], v176 offset:16640
	s_waitcnt lgkmcnt(1)
	v_mfma_f32_16x16x32_bf16 v[132:135], v[172:175], v[198:201], v[132:135]
	s_waitcnt lgkmcnt(0)
	v_mfma_f32_16x16x32_bf16 v[128:131], v[194:197], v[198:201], v[128:131]
	v_mfma_f32_16x16x32_bf16 v[104:107], v[172:175], v[202:205], v[104:107]
	v_mfma_f32_16x16x32_bf16 v[96:99], v[194:197], v[202:205], v[96:99]
	v_mfma_f32_16x16x32_bf16 v[72:75], v[172:175], v[206:209], v[72:75]
	v_mfma_f32_16x16x32_bf16 v[64:67], v[194:197], v[206:209], v[64:67]
	v_mfma_f32_16x16x32_bf16 v[44:47], v[172:175], v[212:215], v[44:47]
	ds_read_b128 v[172:175], v176 offset:17920
	v_mfma_f32_16x16x32_bf16 v[40:43], v[194:197], v[212:215], v[40:43]
	ds_read_b128 v[194:197], v176 offset:19200
	s_waitcnt lgkmcnt(1)
	v_mfma_f32_16x16x32_bf16 v[120:123], v[172:175], v[198:201], v[120:123]
	s_waitcnt lgkmcnt(0)
	v_mfma_f32_16x16x32_bf16 v[112:115], v[194:197], v[198:201], v[112:115]
	v_mfma_f32_16x16x32_bf16 v[88:91], v[172:175], v[202:205], v[88:91]
	v_mfma_f32_16x16x32_bf16 v[80:83], v[194:197], v[202:205], v[80:83]
	v_mfma_f32_16x16x32_bf16 v[56:59], v[172:175], v[206:209], v[56:59]
	v_mfma_f32_16x16x32_bf16 v[48:51], v[194:197], v[206:209], v[48:51]
	v_mfma_f32_16x16x32_bf16 v[36:39], v[172:175], v[212:215], v[36:39]
	v_mfma_f32_16x16x32_bf16 v[32:35], v[194:197], v[212:215], v[32:35]
	s_setprio 0
	v_lshl_add_u64 v[164:165], v[164:165], 0, s[38:39]
	s_cmp_eq_u32 s51, 30
	v_lshl_add_u64 v[166:167], v[166:167], 0, s[28:29]
	s_barrier
	s_cbranch_scc0 .LBB0_460
; #define G_LOAD(kt_) do { \
;     if constexpr (AF32) { _Pragma("unroll") for (int i = 0; i < 4; ++i) ld16_sc1(ra[i], Af + (size_t)i * 32 * lda + (kt_) * 32); } \
;     else { _Pragma("unroll") for (int i = 0; i < 2; ++i) ld16_sc1(rab[i], Ab + (size_t)i * 64 * lda + (kt_) * 32); } \
;     _Pragma("unroll") for (int i = 0; i < 4; ++i) ld16_sc1(rb[i], Bp + (size_t)(kt_) * bstep + i * 2048); } while (0)
; template <bool AF32, class Epi>
; __device__ __forceinline__ void gemm_tile(unsigned char* smem, const void* Ap, int lda, const bf16_t* WT, int N, int K, const Epi& epi, int m0, int n0,
;                                           GPre& pr, bool preloaded, const void* nAp, int nn0, bool has_next) {
;     ...
;   if (!preloaded) G_LOAD(0);
;   G_STORE(0);
;   if (nk > 1) G_LOAD(1);
;   __syncthreads();
;   for (int kt = 0; kt < nk; ++kt) {
;     const int cur = kt & 1;
;     if (kt + 1 < nk) G_STORE(cur ^ 1);
;     if (kt + 2 < nk) G_LOAD(kt + 2);
;     const bf16_t* a_s = sbase + cur * G_STAGE + (wr * 64 + l15) * GLD + quad * 8;
;     const bf16_t* b_s = sbase + cur * G_STAGE + 128 * GLD + (wc * 128 + l15) * GLD + quad * 8;
;     __builtin_amdgcn_s_setprio(1);
;     bf16x8 af[4];
; #pragma unroll
;     for (int m = 0; m < 4; ++m) af[m] = *(const bf16x8*)(a_s + m * 16 * GLD);
; #pragma unroll
;     for (int nh = 0; nh < 4; ++nh) {
;       bf16x8 bfr[2];
; #pragma unroll
;       for (int n2 = 0; n2 < 2; ++n2) bfr[n2] = *(const bf16x8*)(b_s + (nh * 2 + n2) * 16 * GLD);
; #pragma unroll
;       for (int m = 0; m < 4; ++m)
; #pragma unroll
;         for (int n2 = 0; n2 < 2; ++n2) acc[m][nh * 2 + n2] = __builtin_amdgcn_mfma_f32_16x16x32_bf16(bfr[n2], af[m], acc[m][nh * 2 + n2], 0, 0, 0);
;     }
;     __builtin_amdgcn_s_setprio(0);
;     __syncthreads();
	s_waitcnt vmcnt(0)
	v_add_u32_e32 v176, v169, v170
	v_cvt_pk_bf16_f32 v164, v28, v29
	v_cvt_pk_bf16_f32 v165, v30, v31
	v_cvt_pk_bf16_f32 v166, v24, v25
	v_cvt_pk_bf16_f32 v167, v26, v27
	ds_write2st64_b64 v161, v[164:165], v[166:167] offset0:60 offset1:65
	v_cvt_pk_bf16_f32 v164, v20, v21
	v_cvt_pk_bf16_f32 v165, v22, v23
	v_cvt_pk_bf16_f32 v166, v16, v17
	v_cvt_pk_bf16_f32 v167, v18, v19
	ds_write2st64_b64 v161, v[164:165], v[166:167] offset0:70 offset1:75
	ds_write_b128 v163, v[0:3] offset:40960
	ds_write_b128 v163, v[4:7] offset:46080
	ds_write_b128 v163, v[8:11] offset:51200
	ds_write_b128 v163, v[12:15] offset:56320
	s_setprio 1
	v_add_u32_e32 v193, v168, v170
	ds_read_b128 v[160:163], v193 offset:10240
	ds_read_b128 v[164:167], v193 offset:11520
	ds_read_b128 v[168:171], v176
	ds_read_b128 v[172:175], v176 offset:1280
	ds_read_b128 v[194:197], v176 offset:2560
	ds_read_b128 v[198:201], v176 offset:3840
	s_waitcnt lgkmcnt(3)
	v_mfma_f32_16x16x32_bf16 v[156:159], v[160:163], v[168:171], v[156:159]
	v_mfma_f32_16x16x32_bf16 v[152:155], v[164:167], v[168:171], v[152:155]
	s_waitcnt lgkmcnt(2)
	v_mfma_f32_16x16x32_bf16 v[140:143], v[160:163], v[172:175], v[140:143]
	v_mfma_f32_16x16x32_bf16 v[136:139], v[164:167], v[172:175], v[136:139]
	s_waitcnt lgkmcnt(1)
	v_mfma_f32_16x16x32_bf16 v[108:111], v[160:163], v[194:197], v[108:111]
	v_mfma_f32_16x16x32_bf16 v[100:103], v[164:167], v[194:197], v[100:103]
	s_waitcnt lgkmcnt(0)
	v_mfma_f32_16x16x32_bf16 v[76:79], v[160:163], v[198:201], v[76:79]
	ds_read_b128 v[160:163], v193 offset:12800
	v_mfma_f32_16x16x32_bf16 v[68:71], v[164:167], v[198:201], v[68:71]
	ds_read_b128 v[164:167], v193 offset:14080
	s_waitcnt lgkmcnt(1)
	v_mfma_f32_16x16x32_bf16 v[148:151], v[160:163], v[168:171], v[148:151]
	s_waitcnt lgkmcnt(0)
	v_mfma_f32_16x16x32_bf16 v[144:147], v[164:167], v[168:171], v[144:147]
	v_mfma_f32_16x16x32_bf16 v[124:127], v[160:163], v[172:175], v[124:127]
	v_mfma_f32_16x16x32_bf16 v[116:119], v[164:167], v[172:175], v[116:119]
	v_mfma_f32_16x16x32_bf16 v[92:95], v[160:163], v[194:197], v[92:95]
	v_mfma_f32_16x16x32_bf16 v[84:87], v[164:167], v[194:197], v[84:87]
	v_mfma_f32_16x16x32_bf16 v[60:63], v[160:163], v[198:201], v[60:63]
	ds_read_b128 v[160:163], v193 offset:15360
	v_mfma_f32_16x16x32_bf16 v[52:55], v[164:167], v[198:201], v[52:55]
	ds_read_b128 v[164:167], v193 offset:16640
	s_waitcnt lgkmcnt(1)
	v_mfma_f32_16x16x32_bf16 v[212:215], v[160:163], v[194:197], v[72:75]
	s_nop 2
	ds_read_b128 v[72:75], v193 offset:19200
	s_waitcnt lgkmcnt(1)
	v_mfma_f32_16x16x32_bf16 v[216:219], v[164:167], v[194:197], v[64:67]
	s_nop 2
	ds_read_b128 v[64:67], v193 offset:17920
	v_mfma_f32_16x16x32_bf16 v[128:131], v[164:167], v[168:171], v[128:131]
	v_mfma_f32_16x16x32_bf16 v[96:99], v[164:167], v[172:175], v[96:99]
	s_waitcnt lgkmcnt(0)
	v_mfma_f32_16x16x32_bf16 v[120:123], v[64:67], v[168:171], v[120:123]
	v_mfma_f32_16x16x32_bf16 v[112:115], v[72:75], v[168:171], v[112:115]
	v_mfma_f32_16x16x32_bf16 v[88:91], v[64:67], v[172:175], v[88:91]
	v_mfma_f32_16x16x32_bf16 v[80:83], v[72:75], v[172:175], v[80:83]
	v_mfma_f32_16x16x32_bf16 v[48:51], v[72:75], v[194:197], v[48:51]
	v_mfma_f32_16x16x32_bf16 v[202:205], v[160:163], v[168:171], v[132:135]
	v_mfma_f32_16x16x32_bf16 v[206:209], v[160:163], v[172:175], v[104:107]
	v_mfma_f32_16x16x32_bf16 v[44:47], v[160:163], v[198:201], v[44:47]
	v_mfma_f32_16x16x32_bf16 v[40:43], v[164:167], v[198:201], v[40:43]
	v_mfma_f32_16x16x32_bf16 v[220:223], v[64:67], v[194:197], v[56:59]
	v_mfma_f32_16x16x32_bf16 v[36:39], v[64:67], v[198:201], v[36:39]
	v_mfma_f32_16x16x32_bf16 v[32:35], v[72:75], v[198:201], v[32:35]
	s_setprio 0
	s_barrier
; #define G_LOAD(kt_) do { \
;     if constexpr (AF32) { _Pragma("unroll") for (int i = 0; i < 4; ++i) ld16_sc1(ra[i], Af + (size_t)i * 32 * lda + (kt_) * 32); } \
;     else { _Pragma("unroll") for (int i = 0; i < 2; ++i) ld16_sc1(rab[i], Ab + (size_t)i * 64 * lda + (kt_) * 32); } \
;     _Pragma("unroll") for (int i = 0; i < 4; ++i) ld16_sc1(rb[i], Bp + (size_t)(kt_) * bstep + i * 2048); } while (0)
; template <bool AF32, class Epi>
; __device__ __forceinline__ void gemm_tile(unsigned char* smem, const void* Ap, int lda, const bf16_t* WT, int N, int K, const Epi& epi, int m0, int n0,
;                                           GPre& pr, bool preloaded, const void* nAp, int nn0, bool has_next) {
;     ...
;   for (int kt = 0; kt < nk; ++kt) {
;     const int cur = kt & 1;
;     if (kt + 1 < nk) G_STORE(cur ^ 1);
;     if (kt + 2 < nk) G_LOAD(kt + 2);
;     const bf16_t* a_s = sbase + cur * G_STAGE + (wr * 64 + l15) * GLD + quad * 8;
;     const bf16_t* b_s = sbase + cur * G_STAGE + 128 * GLD + (wc * 128 + l15) * GLD + quad * 8;
;     __builtin_amdgcn_s_setprio(1);
;     bf16x8 af[4];
; #pragma unroll
;     for (int m = 0; m < 4; ++m) af[m] = *(const bf16x8*)(a_s + m * 16 * GLD);
; #pragma unroll
;     for (int nh = 0; nh < 4; ++nh) {
;       bf16x8 bfr[2];
; #pragma unroll
;       for (int n2 = 0; n2 < 2; ++n2) bfr[n2] = *(const bf16x8*)(b_s + (nh * 2 + n2) * 16 * GLD);
; #pragma unroll
;       for (int m = 0; m < 4; ++m)
; #pragma unroll
;         for (int n2 = 0; n2 < 2; ++n2) acc[m][nh * 2 + n2] = __builtin_amdgcn_mfma_f32_16x16x32_bf16(bfr[n2], af[m], acc[m][nh * 2 + n2], 0, 0, 0);
;     }
;     __builtin_amdgcn_s_setprio(0);
;     __syncthreads();
;   }
;   if (has_next) {
;     const float* Af = (const float*)nAp + (size_t)(tid >> 3) * lda + (tid & 7) * 4;
;     const bf16_t* Ab = (const bf16_t*)nAp + (size_t)(tid >> 2) * lda + (tid & 3) * 8;
;     const bf16_t* Bp = WT + (size_t)nn0 * 32 + tid * 8;
;     G_LOAD(0);
;   }
	s_setprio 1
	ds_read_b128 v[56:59], v193 offset:40960
	ds_read_b128 v[64:67], v193 offset:42240
	ds_read_b128 v[194:197], v176 offset:30720
	ds_read_b128 v[198:201], v176 offset:32000
	ds_read_b128 v[224:227], v176 offset:33280
	ds_read_b128 v[228:231], v176 offset:34560
	s_waitcnt lgkmcnt(3)
	v_mfma_f32_16x16x32_bf16 v[172:175], v[56:59], v[194:197], v[156:159]
	v_mfma_f32_16x16x32_bf16 v[164:167], v[64:67], v[194:197], v[152:155]
	s_waitcnt lgkmcnt(2)
	v_mfma_f32_16x16x32_bf16 v[140:143], v[56:59], v[198:201], v[140:143]
	v_mfma_f32_16x16x32_bf16 v[132:135], v[64:67], v[198:201], v[136:139]
	s_waitcnt lgkmcnt(1)
	v_mfma_f32_16x16x32_bf16 v[108:111], v[56:59], v[224:227], v[108:111]
	v_mfma_f32_16x16x32_bf16 v[100:103], v[64:67], v[224:227], v[100:103]
	s_waitcnt lgkmcnt(0)
	v_mfma_f32_16x16x32_bf16 v[76:79], v[56:59], v[228:231], v[76:79]
	ds_read_b128 v[56:59], v193 offset:43520
	v_mfma_f32_16x16x32_bf16 v[72:75], v[64:67], v[228:231], v[68:71]
	ds_read_b128 v[64:67], v193 offset:44800
	s_waitcnt lgkmcnt(1)
	v_mfma_f32_16x16x32_bf16 v[168:171], v[56:59], v[194:197], v[148:151]
	s_waitcnt lgkmcnt(0)
	v_mfma_f32_16x16x32_bf16 v[156:159], v[64:67], v[194:197], v[144:147]
	v_mfma_f32_16x16x32_bf16 v[136:139], v[56:59], v[198:201], v[124:127]
	v_mfma_f32_16x16x32_bf16 v[124:127], v[64:67], v[198:201], v[116:119]
	v_mfma_f32_16x16x32_bf16 v[104:107], v[56:59], v[224:227], v[92:95]
	v_mfma_f32_16x16x32_bf16 v[92:95], v[64:67], v[224:227], v[84:87]
	v_mfma_f32_16x16x32_bf16 v[68:71], v[56:59], v[228:231], v[60:63]
	ds_read_b128 v[56:59], v193 offset:46080
	v_mfma_f32_16x16x32_bf16 v[64:67], v[64:67], v[228:231], v[52:55]
	s_nop 2
	ds_read_b128 v[52:55], v193 offset:47360
	s_waitcnt lgkmcnt(1)
	v_mfma_f32_16x16x32_bf16 v[160:163], v[56:59], v[194:197], v[202:205]
	s_waitcnt lgkmcnt(0)
	v_mfma_f32_16x16x32_bf16 v[148:151], v[52:55], v[194:197], v[128:131]
	v_mfma_f32_16x16x32_bf16 v[128:131], v[56:59], v[198:201], v[206:209]
	v_mfma_f32_16x16x32_bf16 v[116:119], v[52:55], v[198:201], v[96:99]
	v_mfma_f32_16x16x32_bf16 v[96:99], v[56:59], v[224:227], v[212:215]
	v_mfma_f32_16x16x32_bf16 v[60:63], v[56:59], v[228:231], v[44:47]
	s_nop 2
	ds_read_b128 v[44:47], v193 offset:48640
	v_mfma_f32_16x16x32_bf16 v[56:59], v[52:55], v[228:231], v[40:43]
	s_nop 2
	ds_read_b128 v[40:43], v193 offset:49920
	v_mfma_f32_16x16x32_bf16 v[84:87], v[52:55], v[224:227], v[216:219]
	s_waitcnt lgkmcnt(1)
	v_mfma_f32_16x16x32_bf16 v[152:155], v[44:47], v[194:197], v[120:123]
	s_waitcnt lgkmcnt(0)
	v_mfma_f32_16x16x32_bf16 v[144:147], v[40:43], v[194:197], v[112:115]
	v_mfma_f32_16x16x32_bf16 v[120:123], v[44:47], v[198:201], v[88:91]
	v_mfma_f32_16x16x32_bf16 v[112:115], v[40:43], v[198:201], v[80:83]
	v_mfma_f32_16x16x32_bf16 v[88:91], v[44:47], v[224:227], v[220:223]
	v_mfma_f32_16x16x32_bf16 v[80:83], v[40:43], v[224:227], v[48:51]
	v_mfma_f32_16x16x32_bf16 v[52:55], v[44:47], v[228:231], v[36:39]
	v_mfma_f32_16x16x32_bf16 v[48:51], v[40:43], v[228:231], v[32:35]
	s_and_b64 vcc, exec, s[6:7]
	s_barrier
	s_cbranch_vccz .LBB0_463
	s_ashr_i32 s53, s52, 31
	s_lshl_b64 s[6:7], s[52:53], 19
	s_add_u32 s6, s12, s6
	s_addc_u32 s7, s13, s7
	s_lshl_b32 s52, s68, 8
	v_lshl_add_u64 v[0:1], v[188:189], 2, s[6:7]
	v_lshlrev_b32_e32 v176, 2, v190
	s_ashr_i32 s53, s52, 31
	v_lshl_add_u64 v[0:1], v[0:1], 0, v[176:177]
	s_lshl_b64 s[6:7], s[52:53], 6
	global_load_dwordx4 v[40:43], v[0:1], off sc1
	s_add_u32 s6, s2, s6
	v_lshl_add_u64 v[2:3], v[0:1], 0, s[16:17]
	global_load_dwordx4 v[44:47], v[2:3], off sc1
	s_addc_u32 s7, s33, s7
	v_lshl_add_u64 v[2:3], v[0:1], 0, s[18:19]
	global_load_dwordx4 v[32:35], v[2:3], off sc1
	v_lshl_add_u64 v[0:1], v[0:1], 0, s[20:21]
	global_load_dwordx4 v[36:39], v[0:1], off sc1
	v_lshl_add_u64 v[12:13], v[184:185], 1, s[6:7]
	global_load_dwordx4 v[0:3], v[12:13], off sc1
	v_lshl_add_u64 v[4:5], v[12:13], 0, s[22:23]
	global_load_dwordx4 v[4:7], v[4:5], off sc1
	v_lshl_add_u64 v[8:9], v[12:13], 0, s[24:25]
	global_load_dwordx4 v[8:11], v[8:9], off sc1
	v_lshl_add_u64 v[12:13], v[12:13], 0, s[26:27]
	global_load_dwordx4 v[12:15], v[12:13], off sc1
	s_branch .LBB0_464

; #define G_LOAD(kt_) do { \
;     if constexpr (AF32) { _Pragma("unroll") for (int i = 0; i < 4; ++i) ld16_sc1(ra[i], Af + (size_t)i * 32 * lda + (kt_) * 32); } \
;     else { _Pragma("unroll") for (int i = 0; i < 2; ++i) ld16_sc1(rab[i], Ab + (size_t)i * 64 * lda + (kt_) * 32); } \
;     _Pragma("unroll") for (int i = 0; i < 4; ++i) ld16_sc1(rb[i], Bp + (size_t)(kt_) * bstep + i * 2048); } while (0)
; template <bool AF32, class Epi>
; __device__ __forceinline__ void gemm_tile(unsigned char* smem, const void* Ap, int lda, const bf16_t* WT, int N, int K, const Epi& epi, int m0, int n0,
;                                           GPre& pr, bool preloaded, const void* nAp, int nn0, bool has_next) {
;     ...
;   if (!preloaded) G_LOAD(0);
;   G_STORE(0);
;   if (nk > 1) G_LOAD(1);
;   __syncthreads();
;   for (int kt = 0; kt < nk; ++kt) {
;     const int cur = kt & 1;
;     if (kt + 1 < nk) G_STORE(cur ^ 1);
;     if (kt + 2 < nk) G_LOAD(kt + 2);
;     const bf16_t* a_s = sbase + cur * G_STAGE + (wr * 64 + l15) * GLD + quad * 8;
;     const bf16_t* b_s = sbase + cur * G_STAGE + 128 * GLD + (wc * 128 + l15) * GLD + quad * 8;
;     __builtin_amdgcn_s_setprio(1);
;     bf16x8 af[4];
; #pragma unroll
;     for (int m = 0; m < 4; ++m) af[m] = *(const bf16x8*)(a_s + m * 16 * GLD);
; #pragma unroll
;     for (int nh = 0; nh < 4; ++nh) {
;       bf16x8 bfr[2];
; #pragma unroll
;       for (int n2 = 0; n2 < 2; ++n2) bfr[n2] = *(const bf16x8*)(b_s + (nh * 2 + n2) * 16 * GLD);
; #pragma unroll
;       for (int m = 0; m < 4; ++m)
; #pragma unroll
;         for (int n2 = 0; n2 < 2; ++n2) acc[m][nh * 2 + n2] = __builtin_amdgcn_mfma_f32_16x16x32_bf16(bfr[n2], af[m], acc[m][nh * 2 + n2], 0, 0, 0);
;     }
;     __builtin_amdgcn_s_setprio(0);
;     __syncthreads();
;   }
.LBB0_678:
	s_and_b32 s3, s49, 1
	s_waitcnt vmcnt(0)
	s_xor_b32 s50, s3, 1
	s_mulk_i32 s50, 0x7800
	v_lshl_add_u32 v176, v162, 1, s50
	ds_write_b128 v176, v[0:3] offset:10240
	ds_write_b128 v176, v[4:7] offset:15360
	ds_write_b128 v176, v[8:11] offset:20480
	ds_write_b128 v176, v[12:15] offset:25600
	s_setprio 2
	global_load_dwordx4 v[0:3], v[164:165], off sc1
	v_lshl_add_u64 v[196:197], v[164:165], 0, s[20:21]
	global_load_dwordx4 v[4:7], v[196:197], off sc1
	v_lshl_add_u64 v[198:199], v[164:165], 0, s[22:23]
	global_load_dwordx4 v[8:11], v[198:199], off sc1
	v_lshl_add_u64 v[200:201], v[164:165], 0, s[24:25]
	global_load_dwordx4 v[12:15], v[200:201], off sc1
	s_setprio 0
	v_cvt_pk_bf16_f32 v202, v44, v45
	v_mov_b32_e32 v205, v44
	v_mov_b32_e32 v44, v41
	v_lshl_add_u32 v171, v160, 1, s50
	v_cvt_pk_bf16_f32 v203, v46, v47
	v_mov_b32_e32 v204, v40
	v_mov_b32_e32 v206, v42
	v_mov_b32_e32 v207, v46
	v_mov_b32_e32 v46, v43
	v_cvt_pk_bf16_f32 v40, v40, v41
	v_cvt_pk_bf16_f32 v41, v42, v43
	v_cvt_pk_bf16_f32 v42, v36, v37
	v_cvt_pk_bf16_f32 v43, v38, v39
	v_mov_b32_e32 v208, v32
	v_mov_b32_e32 v209, v36
	v_mov_b32_e32 v36, v33
	v_mov_b32_e32 v212, v34
	v_mov_b32_e32 v213, v38
	v_mov_b32_e32 v38, v35
	v_cvt_pk_bf16_f32 v32, v32, v33
	v_cvt_pk_bf16_f32 v33, v34, v35
	v_pk_mul_f32 v[34:35], v[44:45], v[44:45]
	ds_write2st64_b64 v171, v[202:203], v[40:41] offset1:5
	ds_write2st64_b64 v171, v[42:43], v[32:33] offset0:10 offset1:15
	v_pk_fma_f32 v[216:217], v[204:205], v[204:205], v[34:35]
	v_pk_mul_f32 v[36:37], v[36:37], v[36:37]
	v_pk_fma_f32 v[216:217], v[206:207], v[206:207], v[216:217]
	v_pk_fma_f32 v[218:219], v[208:209], v[208:209], v[36:37]
	v_pk_fma_f32 v[202:203], v[46:47], v[46:47], v[216:217]
	s_setprio 2
	global_load_dwordx4 v[44:47], v[166:167], off sc1
	v_lshl_add_u64 v[172:173], v[166:167], 0, s[14:15]
	v_pk_fma_f32 v[218:219], v[212:213], v[212:213], v[218:219]
	global_load_dwordx4 v[40:43], v[172:173], off sc1
	v_lshl_add_u64 v[174:175], v[166:167], 0, s[16:17]
	v_pk_fma_f32 v[204:205], v[38:39], v[38:39], v[218:219]
	global_load_dwordx4 v[36:39], v[174:175], off sc1
	v_lshl_add_u64 v[194:195], v[166:167], 0, s[18:19]
	global_load_dwordx4 v[32:35], v[194:195], off sc1
	s_setprio 0
	s_add_i32 s49, s49, 1
	s_mulk_i32 s3, 0x7800
	v_pk_add_f32 v[184:185], v[184:185], v[202:203]
	v_pk_add_f32 v[180:181], v[180:181], v[204:205]
	v_add3_u32 v171, s3, v169, v170
	s_setprio 1
	v_add3_u32 v176, s3, v168, v170
	ds_read_b128 v[172:175], v176 offset:10240
	ds_read_b128 v[194:197], v176 offset:11520
	ds_read_b128 v[198:201], v171
	ds_read_b128 v[202:205], v171 offset:1280
	ds_read_b128 v[206:209], v171 offset:2560
	ds_read_b128 v[212:215], v171 offset:3840
	s_waitcnt lgkmcnt(3)
	v_mfma_f32_16x16x32_bf16 v[156:159], v[172:175], v[198:201], v[156:159]
	v_mfma_f32_16x16x32_bf16 v[152:155], v[194:197], v[198:201], v[152:155]
	s_waitcnt lgkmcnt(2)
	v_mfma_f32_16x16x32_bf16 v[140:143], v[172:175], v[202:205], v[140:143]
	v_mfma_f32_16x16x32_bf16 v[136:139], v[194:197], v[202:205], v[136:139]
	s_waitcnt lgkmcnt(1)
	v_mfma_f32_16x16x32_bf16 v[108:111], v[172:175], v[206:209], v[108:111]
	v_mfma_f32_16x16x32_bf16 v[100:103], v[194:197], v[206:209], v[100:103]
	s_waitcnt lgkmcnt(0)
	v_mfma_f32_16x16x32_bf16 v[76:79], v[172:175], v[212:215], v[76:79]
	ds_read_b128 v[172:175], v176 offset:12800
	v_mfma_f32_16x16x32_bf16 v[68:71], v[194:197], v[212:215], v[68:71]
	ds_read_b128 v[194:197], v176 offset:14080
	s_waitcnt lgkmcnt(1)
	v_mfma_f32_16x16x32_bf16 v[148:151], v[172:175], v[198:201], v[148:151]
	s_waitcnt lgkmcnt(0)
	v_mfma_f32_16x16x32_bf16 v[144:147], v[194:197], v[198:201], v[144:147]
	v_mfma_f32_16x16x32_bf16 v[124:127], v[172:175], v[202:205], v[124:127]
	v_mfma_f32_16x16x32_bf16 v[116:119], v[194:197], v[202:205], v[116:119]
	v_mfma_f32_16x16x32_bf16 v[92:95], v[172:175], v[206:209], v[92:95]
	v_mfma_f32_16x16x32_bf16 v[84:87], v[194:197], v[206:209], v[84:87]
	v_mfma_f32_16x16x32_bf16 v[60:63], v[172:175], v[212:215], v[60:63]
	ds_read_b128 v[172:175], v176 offset:15360
	v_mfma_f32_16x16x32_bf16 v[52:55], v[194:197], v[212:215], v[52:55]
	ds_read_b128 v[194:197], v176 offset:16640
	s_waitcnt lgkmcnt(1)
	v_mfma_f32_16x16x32_bf16 v[132:135], v[172:175], v[198:201], v[132:135]
	s_waitcnt lgkmcnt(0)
	v_mfma_f32_16x16x32_bf16 v[128:131], v[194:197], v[198:201], v[128:131]
	v_mfma_f32_16x16x32_bf16 v[104:107], v[172:175], v[202:205], v[104:107]
	v_mfma_f32_16x16x32_bf16 v[96:99], v[194:197], v[202:205], v[96:99]
	v_mfma_f32_16x16x32_bf16 v[72:75], v[172:175], v[206:209], v[72:75]
	v_mfma_f32_16x16x32_bf16 v[64:67], v[194:197], v[206:209], v[64:67]
	v_mfma_f32_16x16x32_bf16 v[28:31], v[172:175], v[212:215], v[28:31]
	ds_read_b128 v[172:175], v176 offset:17920
	v_mfma_f32_16x16x32_bf16 v[24:27], v[194:197], v[212:215], v[24:27]
	ds_read_b128 v[194:197], v176 offset:19200
	s_waitcnt lgkmcnt(1)
	v_mfma_f32_16x16x32_bf16 v[120:123], v[172:175], v[198:201], v[120:123]
	s_waitcnt lgkmcnt(0)
	v_mfma_f32_16x16x32_bf16 v[112:115], v[194:197], v[198:201], v[112:115]
	v_mfma_f32_16x16x32_bf16 v[88:91], v[172:175], v[202:205], v[88:91]
	v_mfma_f32_16x16x32_bf16 v[80:83], v[194:197], v[202:205], v[80:83]
	v_mfma_f32_16x16x32_bf16 v[56:59], v[172:175], v[206:209], v[56:59]
	v_mfma_f32_16x16x32_bf16 v[48:51], v[194:197], v[206:209], v[48:51]
	v_mfma_f32_16x16x32_bf16 v[20:23], v[172:175], v[212:215], v[20:23]
	v_mfma_f32_16x16x32_bf16 v[16:19], v[194:197], v[212:215], v[16:19]
	s_setprio 0
	v_lshl_add_u64 v[164:165], v[164:165], 0, s[36:37]
	s_cmp_eq_u32 s49, 30
	v_lshl_add_u64 v[166:167], v[166:167], 0, s[26:27]
	s_barrier
	s_cbranch_scc0 .LBB0_678
; #define G_LOAD(kt_) do { \
;     if constexpr (AF32) { _Pragma("unroll") for (int i = 0; i < 4; ++i) ld16_sc1(ra[i], Af + (size_t)i * 32 * lda + (kt_) * 32); } \
;     else { _Pragma("unroll") for (int i = 0; i < 2; ++i) ld16_sc1(rab[i], Ab + (size_t)i * 64 * lda + (kt_) * 32); } \
;     _Pragma("unroll") for (int i = 0; i < 4; ++i) ld16_sc1(rb[i], Bp + (size_t)(kt_) * bstep + i * 2048); } while (0)
; template <bool AF32, class Epi>
; __device__ __forceinline__ void gemm_tile(unsigned char* smem, const void* Ap, int lda, const bf16_t* WT, int N, int K, const Epi& epi, int m0, int n0,
;                                           GPre& pr, bool preloaded, const void* nAp, int nn0, bool has_next) {
;     ...
;   if (!preloaded) G_LOAD(0);
;   G_STORE(0);
;   if (nk > 1) G_LOAD(1);
;   __syncthreads();
;   for (int kt = 0; kt < nk; ++kt) {
;     const int cur = kt & 1;
;     if (kt + 1 < nk) G_STORE(cur ^ 1);
;     if (kt + 2 < nk) G_LOAD(kt + 2);
;     const bf16_t* a_s = sbase + cur * G_STAGE + (wr * 64 + l15) * GLD + quad * 8;
;     const bf16_t* b_s = sbase + cur * G_STAGE + 128 * GLD + (wc * 128 + l15) * GLD + quad * 8;
;     __builtin_amdgcn_s_setprio(1);
;     bf16x8 af[4];
; #pragma unroll
;     for (int m = 0; m < 4; ++m) af[m] = *(const bf16x8*)(a_s + m * 16 * GLD);
; #pragma unroll
;     for (int nh = 0; nh < 4; ++nh) {
;       bf16x8 bfr[2];
; #pragma unroll
;       for (int n2 = 0; n2 < 2; ++n2) bfr[n2] = *(const bf16x8*)(b_s + (nh * 2 + n2) * 16 * GLD);
; #pragma unroll
;       for (int m = 0; m < 4; ++m)
; #pragma unroll
;         for (int n2 = 0; n2 < 2; ++n2) acc[m][nh * 2 + n2] = __builtin_amdgcn_mfma_f32_16x16x32_bf16(bfr[n2], af[m], acc[m][nh * 2 + n2], 0, 0, 0);
;     }
;     __builtin_amdgcn_s_setprio(0);
;     __syncthreads();
	s_waitcnt vmcnt(0)
	v_add_u32_e32 v176, v169, v170
	v_cvt_pk_bf16_f32 v164, v44, v45
	v_cvt_pk_bf16_f32 v165, v46, v47
	v_cvt_pk_bf16_f32 v166, v40, v41
	v_cvt_pk_bf16_f32 v167, v42, v43
	ds_write2st64_b64 v161, v[164:165], v[166:167] offset0:60 offset1:65
	v_cvt_pk_bf16_f32 v164, v36, v37
	v_cvt_pk_bf16_f32 v165, v38, v39
	v_cvt_pk_bf16_f32 v166, v32, v33
	v_cvt_pk_bf16_f32 v167, v34, v35
	ds_write2st64_b64 v161, v[164:165], v[166:167] offset0:70 offset1:75
	ds_write_b128 v163, v[0:3] offset:40960
	ds_write_b128 v163, v[4:7] offset:46080
	ds_write_b128 v163, v[8:11] offset:51200
	ds_write_b128 v163, v[12:15] offset:56320
	s_setprio 1
	v_add_u32_e32 v193, v168, v170
	ds_read_b128 v[160:163], v193 offset:10240
	ds_read_b128 v[164:167], v193 offset:11520
	ds_read_b128 v[168:171], v176
	ds_read_b128 v[172:175], v176 offset:1280
	ds_read_b128 v[194:197], v176 offset:2560
	ds_read_b128 v[198:201], v176 offset:3840
	s_waitcnt lgkmcnt(3)
	v_mfma_f32_16x16x32_bf16 v[156:159], v[160:163], v[168:171], v[156:159]
	v_mfma_f32_16x16x32_bf16 v[152:155], v[164:167], v[168:171], v[152:155]
	s_waitcnt lgkmcnt(2)
	v_mfma_f32_16x16x32_bf16 v[140:143], v[160:163], v[172:175], v[140:143]
	v_mfma_f32_16x16x32_bf16 v[136:139], v[164:167], v[172:175], v[136:139]
	s_waitcnt lgkmcnt(1)
	v_mfma_f32_16x16x32_bf16 v[108:111], v[160:163], v[194:197], v[108:111]
	v_mfma_f32_16x16x32_bf16 v[100:103], v[164:167], v[194:197], v[100:103]
	s_waitcnt lgkmcnt(0)
	v_mfma_f32_16x16x32_bf16 v[76:79], v[160:163], v[198:201], v[76:79]
	ds_read_b128 v[160:163], v193 offset:12800
	v_mfma_f32_16x16x32_bf16 v[68:71], v[164:167], v[198:201], v[68:71]
	ds_read_b128 v[164:167], v193 offset:14080
	s_waitcnt lgkmcnt(1)
	v_mfma_f32_16x16x32_bf16 v[148:151], v[160:163], v[168:171], v[148:151]
	s_waitcnt lgkmcnt(0)
	v_mfma_f32_16x16x32_bf16 v[144:147], v[164:167], v[168:171], v[144:147]
	v_mfma_f32_16x16x32_bf16 v[124:127], v[160:163], v[172:175], v[124:127]
	v_mfma_f32_16x16x32_bf16 v[116:119], v[164:167], v[172:175], v[116:119]
	v_mfma_f32_16x16x32_bf16 v[92:95], v[160:163], v[194:197], v[92:95]
	v_mfma_f32_16x16x32_bf16 v[84:87], v[164:167], v[194:197], v[84:87]
	v_mfma_f32_16x16x32_bf16 v[60:63], v[160:163], v[198:201], v[60:63]
	ds_read_b128 v[160:163], v193 offset:15360
	v_mfma_f32_16x16x32_bf16 v[52:55], v[164:167], v[198:201], v[52:55]
	ds_read_b128 v[164:167], v193 offset:16640
	s_waitcnt lgkmcnt(1)
	v_mfma_f32_16x16x32_bf16 v[220:223], v[160:163], v[194:197], v[72:75]
	s_nop 2
	ds_read_b128 v[72:75], v193 offset:19200
	s_waitcnt lgkmcnt(1)
	v_mfma_f32_16x16x32_bf16 v[224:227], v[164:167], v[194:197], v[64:67]
	s_nop 2
	ds_read_b128 v[64:67], v193 offset:17920
	s_waitcnt lgkmcnt(1)
	v_mfma_f32_16x16x32_bf16 v[112:115], v[72:75], v[168:171], v[112:115]
	v_mfma_f32_16x16x32_bf16 v[80:83], v[72:75], v[172:175], v[80:83]
	v_mfma_f32_16x16x32_bf16 v[48:51], v[72:75], v[194:197], v[48:51]
	v_mfma_f32_16x16x32_bf16 v[202:205], v[160:163], v[168:171], v[132:135]
	v_mfma_f32_16x16x32_bf16 v[206:209], v[164:167], v[168:171], v[128:131]
	v_mfma_f32_16x16x32_bf16 v[212:215], v[160:163], v[172:175], v[104:107]
	v_mfma_f32_16x16x32_bf16 v[216:219], v[164:167], v[172:175], v[96:99]
	v_mfma_f32_16x16x32_bf16 v[28:31], v[160:163], v[198:201], v[28:31]
	v_mfma_f32_16x16x32_bf16 v[24:27], v[164:167], v[198:201], v[24:27]
	s_waitcnt lgkmcnt(0)
	v_mfma_f32_16x16x32_bf16 v[228:231], v[64:67], v[168:171], v[120:123]
	v_mfma_f32_16x16x32_bf16 v[232:235], v[64:67], v[172:175], v[88:91]
	v_mfma_f32_16x16x32_bf16 v[236:239], v[64:67], v[194:197], v[56:59]
	v_mfma_f32_16x16x32_bf16 v[20:23], v[64:67], v[198:201], v[20:23]
	v_mfma_f32_16x16x32_bf16 v[16:19], v[72:75], v[198:201], v[16:19]
	s_setprio 0
	s_barrier
; #define G_LOAD(kt_) do { \
;     if constexpr (AF32) { _Pragma("unroll") for (int i = 0; i < 4; ++i) ld16_sc1(ra[i], Af + (size_t)i * 32 * lda + (kt_) * 32); } \
;     else { _Pragma("unroll") for (int i = 0; i < 2; ++i) ld16_sc1(rab[i], Ab + (size_t)i * 64 * lda + (kt_) * 32); } \
;     _Pragma("unroll") for (int i = 0; i < 4; ++i) ld16_sc1(rb[i], Bp + (size_t)(kt_) * bstep + i * 2048); } while (0)
; template <bool AF32, class Epi>
; __device__ __forceinline__ void gemm_tile(unsigned char* smem, const void* Ap, int lda, const bf16_t* WT, int N, int K, const Epi& epi, int m0, int n0,
;                                           GPre& pr, bool preloaded, const void* nAp, int nn0, bool has_next) {
;     ...
;   for (int kt = 0; kt < nk; ++kt) {
;     const int cur = kt & 1;
;     if (kt + 1 < nk) G_STORE(cur ^ 1);
;     if (kt + 2 < nk) G_LOAD(kt + 2);
;     const bf16_t* a_s = sbase + cur * G_STAGE + (wr * 64 + l15) * GLD + quad * 8;
;     const bf16_t* b_s = sbase + cur * G_STAGE + 128 * GLD + (wc * 128 + l15) * GLD + quad * 8;
;     __builtin_amdgcn_s_setprio(1);
;     bf16x8 af[4];
; #pragma unroll
;     for (int m = 0; m < 4; ++m) af[m] = *(const bf16x8*)(a_s + m * 16 * GLD);
; #pragma unroll
;     for (int nh = 0; nh < 4; ++nh) {
;       bf16x8 bfr[2];
; #pragma unroll
;       for (int n2 = 0; n2 < 2; ++n2) bfr[n2] = *(const bf16x8*)(b_s + (nh * 2 + n2) * 16 * GLD);
; #pragma unroll
;       for (int m = 0; m < 4; ++m)
; #pragma unroll
;         for (int n2 = 0; n2 < 2; ++n2) acc[m][nh * 2 + n2] = __builtin_amdgcn_mfma_f32_16x16x32_bf16(bfr[n2], af[m], acc[m][nh * 2 + n2], 0, 0, 0);
;     }
;     __builtin_amdgcn_s_setprio(0);
;     __syncthreads();
;   }
;   if (has_next) {
;     const float* Af = (const float*)nAp + (size_t)(tid >> 3) * lda + (tid & 7) * 4;
;     const bf16_t* Ab = (const bf16_t*)nAp + (size_t)(tid >> 2) * lda + (tid & 3) * 8;
;     const bf16_t* Bp = WT + (size_t)nn0 * 32 + tid * 8;
;     G_LOAD(0);
;   }
	s_setprio 1
	ds_read_b128 v[56:59], v193 offset:40960
	ds_read_b128 v[64:67], v193 offset:42240
	ds_read_b128 v[194:197], v176 offset:30720
	ds_read_b128 v[198:201], v176 offset:32000
	ds_read_b128 v[240:243], v176 offset:33280
	ds_read_b128 v[244:247], v176 offset:34560
	s_waitcnt lgkmcnt(3)
	v_mfma_f32_16x16x32_bf16 v[172:175], v[56:59], v[194:197], v[156:159]
	v_mfma_f32_16x16x32_bf16 v[168:171], v[64:67], v[194:197], v[152:155]
	s_waitcnt lgkmcnt(2)
	v_mfma_f32_16x16x32_bf16 v[140:143], v[56:59], v[198:201], v[140:143]
	v_mfma_f32_16x16x32_bf16 v[136:139], v[64:67], v[198:201], v[136:139]
	s_waitcnt lgkmcnt(1)
	v_mfma_f32_16x16x32_bf16 v[108:111], v[56:59], v[240:243], v[108:111]
	v_mfma_f32_16x16x32_bf16 v[104:107], v[64:67], v[240:243], v[100:103]
	s_waitcnt lgkmcnt(0)
	v_mfma_f32_16x16x32_bf16 v[76:79], v[56:59], v[244:247], v[76:79]
	ds_read_b128 v[56:59], v193 offset:43520
	v_mfma_f32_16x16x32_bf16 v[72:75], v[64:67], v[244:247], v[68:71]
	ds_read_b128 v[64:67], v193 offset:44800
	s_waitcnt lgkmcnt(1)
	v_mfma_f32_16x16x32_bf16 v[164:167], v[56:59], v[194:197], v[148:151]
	s_waitcnt lgkmcnt(0)
	v_mfma_f32_16x16x32_bf16 v[160:163], v[64:67], v[194:197], v[144:147]
	v_mfma_f32_16x16x32_bf16 v[132:135], v[56:59], v[198:201], v[124:127]
	v_mfma_f32_16x16x32_bf16 v[128:131], v[64:67], v[198:201], v[116:119]
	v_mfma_f32_16x16x32_bf16 v[100:103], v[56:59], v[240:243], v[92:95]
	v_mfma_f32_16x16x32_bf16 v[96:99], v[64:67], v[240:243], v[84:87]
	v_mfma_f32_16x16x32_bf16 v[68:71], v[56:59], v[244:247], v[60:63]
	ds_read_b128 v[56:59], v193 offset:46080
	v_mfma_f32_16x16x32_bf16 v[64:67], v[64:67], v[244:247], v[52:55]
	s_nop 2
	ds_read_b128 v[52:55], v193 offset:47360
	s_waitcnt lgkmcnt(1)
	v_mfma_f32_16x16x32_bf16 v[156:159], v[56:59], v[194:197], v[202:205]
	v_mfma_f32_16x16x32_bf16 v[124:127], v[56:59], v[198:201], v[212:215]
	v_mfma_f32_16x16x32_bf16 v[92:95], v[56:59], v[240:243], v[220:223]
	v_mfma_f32_16x16x32_bf16 v[60:63], v[56:59], v[244:247], v[28:31]
	s_nop 2
	ds_read_b128 v[28:31], v193 offset:48640
	s_waitcnt lgkmcnt(1)
	v_mfma_f32_16x16x32_bf16 v[56:59], v[52:55], v[244:247], v[24:27]
	s_nop 2
	ds_read_b128 v[24:27], v193 offset:49920
	v_mfma_f32_16x16x32_bf16 v[152:155], v[52:55], v[194:197], v[206:209]
	v_mfma_f32_16x16x32_bf16 v[120:123], v[52:55], v[198:201], v[216:219]
	v_mfma_f32_16x16x32_bf16 v[88:91], v[52:55], v[240:243], v[224:227]
	s_waitcnt lgkmcnt(1)
	v_mfma_f32_16x16x32_bf16 v[148:151], v[28:31], v[194:197], v[228:231]
	s_waitcnt lgkmcnt(0)
	v_mfma_f32_16x16x32_bf16 v[144:147], v[24:27], v[194:197], v[112:115]
	v_mfma_f32_16x16x32_bf16 v[116:119], v[28:31], v[198:201], v[232:235]
	v_mfma_f32_16x16x32_bf16 v[112:115], v[24:27], v[198:201], v[80:83]
	v_mfma_f32_16x16x32_bf16 v[84:87], v[28:31], v[240:243], v[236:239]
	v_mfma_f32_16x16x32_bf16 v[80:83], v[24:27], v[240:243], v[48:51]
	v_mfma_f32_16x16x32_bf16 v[52:55], v[28:31], v[244:247], v[20:23]
	v_mfma_f32_16x16x32_bf16 v[48:51], v[24:27], v[244:247], v[16:19]
	s_and_b64 vcc, exec, s[6:7]
	s_barrier
	s_cbranch_vccz .LBB0_681
	s_ashr_i32 s49, s48, 31
	s_lshl_b64 s[6:7], s[48:49], 19
	s_add_u32 s6, s10, s6
	s_addc_u32 s7, s11, s7
	s_lshl_b32 s48, s65, 8
	v_lshl_add_u64 v[0:1], v[186:187], 2, s[6:7]
	v_lshlrev_b32_e32 v176, 2, v188
	s_ashr_i32 s49, s48, 31
	v_lshl_add_u64 v[0:1], v[0:1], 0, v[176:177]
	s_lshl_b64 s[6:7], s[48:49], 6
	global_load_dwordx4 v[24:27], v[0:1], off sc1
	s_add_u32 s6, s2, s6
	v_lshl_add_u64 v[2:3], v[0:1], 0, s[14:15]
	global_load_dwordx4 v[28:31], v[2:3], off sc1
	s_addc_u32 s7, s33, s7
	v_lshl_add_u64 v[2:3], v[0:1], 0, s[16:17]
	global_load_dwordx4 v[16:19], v[2:3], off sc1
	v_lshl_add_u64 v[0:1], v[0:1], 0, s[18:19]
	global_load_dwordx4 v[20:23], v[0:1], off sc1
	v_lshl_add_u64 v[12:13], v[182:183], 1, s[6:7]
	global_load_dwordx4 v[0:3], v[12:13], off sc1
	v_lshl_add_u64 v[4:5], v[12:13], 0, s[20:21]
	global_load_dwordx4 v[4:7], v[4:5], off sc1
	v_lshl_add_u64 v[8:9], v[12:13], 0, s[22:23]
	global_load_dwordx4 v[8:11], v[8:9], off sc1
	v_lshl_add_u64 v[12:13], v[12:13], 0, s[24:25]
	global_load_dwordx4 v[12:15], v[12:13], off sc1
	s_branch .LBB0_682
